# idsw12
# speedup vs baseline: 1.0067x; 1.0043x over previous
; #define PU_LOAD_A(ID, tt) { _Pragma("unroll") for (int i = 0; i < 4; ++i) ID[i] = *(const int4*)(selE + (size_t)(tt) * 128 + sub * 16 + 4 * i); }
; __device__ void phase_pu(const Params& p, const XcdBarrier& xb) {
;     ...
;   u32x4 u0[16], u1[16], xa0, xb0, xa1, xb1;
;   int4 id_n[4], id_nn[4];
;   int s_c = xi, t_c = wrank;
;   int s_n = s_c, t_n = t_c + nw; if (t_n >= T) { t_n = wrank; s_n += nx; }
;   int s_nn = s_n, t_nn = t_n + nw; if (t_nn >= T) { t_nn = wrank; s_nn += nx; }
;     ...
;   if (s_c < 8) {
;     {
;       int4 id_c[4];
;       PU_LOAD_A(id_c, t_c)
;       PU_LOAD_B(u0, xa0, xb0, id_c, s_c, t_c)
;     }
;     { const int tl_ = (s_n < 8) ? t_n : t_c; PU_LOAD_A(id_n, tl_) }
.LBB0_532:
	s_or_b64 exec, exec, s[2:3]
	v_mov_b32_e32 v0, v197
	s_barrier
	s_cmp_gt_i32 s18, 7
	v_readfirstlane_b32 s2, v0
	s_cbranch_scc1 .LBB0_542
	s_ashr_i32 s2, s2, 6
	s_add_u32 s4, s60, 0x1480000
	s_addc_u32 s5, s61, 0
	s_add_u32 s28, s60, 0xc7a0000
	s_addc_u32 s29, s61, 0
	s_add_u32 s30, s60, 0xd7a0000
	s_addc_u32 s31, s61, 0
	s_lshl_b32 s3, s91, 2
	s_add_i32 s6, s3, s2
	s_lshl_b32 s36, s90, 2
	s_add_i32 s2, s36, s6
	s_cmpk_gt_i32 s2, 0x3fff
	s_cselect_b32 s8, s6, s2
	s_cselect_b32 s2, s33, 0
	s_add_i32 s3, s8, s36
	s_add_i32 s10, s2, s18
	s_cmpk_gt_i32 s3, 0x3fff
	s_cselect_b32 s2, s33, 0
	s_cselect_b32 s11, s6, s3
	s_ashr_i32 s7, s6, 31
	s_add_i32 s17, s2, s10
	s_lshl_b64 s[2:3], s[6:7], 9
	v_lshlrev_b32_e32 v1, 1, v0
	s_add_u32 s2, s20, s2
	v_and_b32_e32 v152, 0x70, v1
	s_addc_u32 s3, s21, s3
	s_waitcnt vmcnt(17)
	v_lshlrev_b32_e32 v76, 2, v152
	v_and_b32_e32 v243, 7, v197
	v_lshl_add_u32 v243, v243, 3, v76
	s_nop 0
	global_load_dwordx4 v[4:7], v76, s[2:3]
	global_load_dwordx4 v[8:11], v76, s[2:3] offset:16
	global_load_dwordx4 v[12:15], v76, s[2:3] offset:32
	global_load_dwordx4 v[16:19], v76, s[2:3] offset:48
	s_lshl_b64 s[2:3], s[6:7], 10
	s_add_u32 s2, s28, s2
	s_addc_u32 s3, s29, s3
	s_lshl_b32 s9, s18, 7
	s_ashr_i32 s16, s9, 31
	s_add_u32 s2, s2, s9
	s_addc_u32 s3, s3, s16
	s_ashr_i32 s19, s18, 31
	s_lshl_b64 s[22:23], s[6:7], 5
	s_add_u32 s7, s30, s22
	s_addc_u32 s9, s31, s23
	s_lshl_b64 s[22:23], s[18:19], 2
	s_add_u32 s22, s7, s22
	v_and_b32_e32 v78, 7, v0
	s_addc_u32 s23, s9, s23
	v_lshlrev_b32_e32 v154, 4, v78
	s_cmp_lt_i32 s10, 8
	v_mov_b32_e32 v155, 0
	global_load_dwordx4 v[0:3], v154, s[2:3]
	global_load_dword v158, v155, s[22:23]
	s_cselect_b32 s2, s8, s6
	s_ashr_i32 s3, s2, 31
	s_lshl_b64 s[2:3], s[2:3], 9
	v_lshl_or_b32 v20, s18, 21, v154
	s_add_u32 s2, s20, s2
	s_addc_u32 s3, s21, s3
	global_load_dwordx2 v[240:241], v243, s[2:3]
	s_mov_b32 s16, s6
	s_mov_b32 s22, s18
	s_waitcnt vmcnt(6)
	v_lshl_add_u32 v79, v4, 7, v20
	s_waitcnt vmcnt(5)
	v_lshl_add_u32 v9, v9, 7, v20
	v_lshl_add_u32 v8, v8, 7, v20
	v_lshl_add_u32 v11, v11, 7, v20
	v_lshl_add_u32 v10, v10, 7, v20
	v_lshl_add_u32 v77, v5, 7, v20
	v_lshl_add_u32 v80, v7, 7, v20
	v_lshl_add_u32 v81, v6, 7, v20
	s_waitcnt vmcnt(4)
	v_lshl_add_u32 v82, v13, 7, v20
	v_lshl_add_u32 v83, v12, 7, v20
	v_lshl_add_u32 v84, v15, 7, v20
	v_lshl_add_u32 v85, v14, 7, v20
	s_waitcnt vmcnt(3)
	v_lshl_add_u32 v86, v17, 7, v20
	v_lshl_add_u32 v87, v16, 7, v20
	v_lshl_add_u32 v88, v19, 7, v20
	v_lshl_add_u32 v89, v18, 7, v20
	global_load_dwordx4 v[64:67], v79, s[4:5]
	global_load_dwordx4 v[60:63], v77, s[4:5]
	global_load_dwordx4 v[56:59], v81, s[4:5]
	global_load_dwordx4 v[52:55], v80, s[4:5]
	global_load_dwordx4 v[48:51], v8, s[4:5]
	global_load_dwordx4 v[44:47], v9, s[4:5]
	global_load_dwordx4 v[40:43], v10, s[4:5]
	global_load_dwordx4 v[36:39], v11, s[4:5]
	global_load_dwordx4 v[32:35], v83, s[4:5]
	global_load_dwordx4 v[28:31], v82, s[4:5]
	global_load_dwordx4 v[24:27], v85, s[4:5]
	global_load_dwordx4 v[20:23], v84, s[4:5]
	global_load_dwordx4 v[16:19], v87, s[4:5]
	global_load_dwordx4 v[12:15], v86, s[4:5]
	global_load_dwordx4 v[4:7], v89, s[4:5]
	global_load_dwordx4 v[8:11], v88, s[4:5]
	v_mov_b32_e32 v77, v155
	v_lshl_add_u64 v[156:157], s[20:21], 0, v[76:77]
	v_cmp_eq_u32_e64 s[2:3], 0, v78
	s_waitcnt vmcnt(0)
	s_nop 0
	s_branch .LBB0_536

.LBB0_536:
	s_cmp_lt_i32 s10, 8
	s_cselect_b32 s26, s8, s16
	s_cselect_b32 s24, s10, s22
	s_ashr_i32 s27, s26, 31
	s_lshl_b64 s[38:39], s[26:27], 10
	s_add_u32 s9, s28, s38
	s_mov_b32 s7, s17
	s_mov_b32 s19, s11
	s_addc_u32 s11, s29, s39
	s_lshl_b32 s17, s24, 7
	s_ashr_i32 s23, s17, 31
	s_add_u32 s38, s9, s17
	s_addc_u32 s39, s11, s23
	s_ashr_i32 s25, s24, 31
	s_lshl_b64 s[26:27], s[26:27], 5
	s_add_u32 s9, s30, s26
	s_waitcnt vmcnt(2)
	ds_swizzle_b32 v108, v240 offset:24
	ds_swizzle_b32 v109, v241 offset:24
	ds_swizzle_b32 v110, v240 offset:56
	ds_swizzle_b32 v111, v241 offset:56
	ds_swizzle_b32 v92, v240 offset:88
	ds_swizzle_b32 v93, v241 offset:88
	ds_swizzle_b32 v94, v240 offset:120
	ds_swizzle_b32 v95, v241 offset:120
	ds_swizzle_b32 v72, v240 offset:152
	ds_swizzle_b32 v73, v241 offset:152
	ds_swizzle_b32 v74, v240 offset:184
	ds_swizzle_b32 v75, v241 offset:184
	ds_swizzle_b32 v68, v240 offset:216
	ds_swizzle_b32 v69, v241 offset:216
	ds_swizzle_b32 v70, v240 offset:248
	ds_swizzle_b32 v71, v241 offset:248
	s_waitcnt lgkmcnt(0)
	s_nop 0
	v_lshl_or_b32 v76, s24, 21, v154
	s_addc_u32 s11, s31, s27
	s_lshl_b64 s[24:25], s[24:25], 2
	s_add_u32 s26, s9, s24
	s_addc_u32 s27, s11, s25
	s_cmp_lt_i32 s7, 8
	s_waitcnt vmcnt(2)
	v_lshl_add_u32 v77, v108, 7, v76
	s_cselect_b64 s[24:25], -1, 0
	v_lshl_add_u32 v78, v109, 7, v76
	global_load_dwordx4 v[148:151], v77, s[4:5]
	global_load_dwordx4 v[144:147], v78, s[4:5]
	v_lshl_add_u32 v77, v110, 7, v76
	v_lshl_add_u64 v[104:105], s[38:39], 0, v[154:155]
	s_and_b64 s[38:39], s[24:25], exec
	v_lshl_add_u32 v78, v111, 7, v76
	global_load_dwordx4 v[140:143], v77, s[4:5]
	global_load_dwordx4 v[136:139], v78, s[4:5]
	v_lshl_add_u32 v77, v92, 7, v76
	s_cselect_b32 s38, s19, s16
	v_lshl_add_u32 v78, v93, 7, v76
	global_load_dwordx4 v[132:135], v77, s[4:5]
	global_load_dwordx4 v[128:131], v78, s[4:5]
	v_lshl_add_u32 v77, v94, 7, v76
	v_lshl_add_u32 v72, v72, 7, v76
	s_ashr_i32 s39, s38, 31
	v_lshl_add_u32 v78, v95, 7, v76
	global_load_dwordx4 v[124:127], v77, s[4:5]
	global_load_dwordx4 v[120:123], v78, s[4:5]
	v_lshl_add_u32 v73, v73, 7, v76
	global_load_dwordx4 v[116:119], v72, s[4:5]
	global_load_dwordx4 v[112:115], v73, s[4:5]
	v_lshl_add_u32 v72, v74, 7, v76
	v_lshl_add_u32 v68, v68, 7, v76
	v_lshl_add_u32 v69, v69, 7, v76
	s_lshl_b64 s[38:39], s[38:39], 9
	v_lshl_add_u32 v73, v75, 7, v76
	global_load_dwordx4 v[100:103], v72, s[4:5]
	global_load_dwordx4 v[96:99], v73, s[4:5]
	global_load_dwordx4 v[88:91], v68, s[4:5]
	global_load_dwordx4 v[84:87], v69, s[4:5]
	v_lshl_add_u32 v68, v70, 7, v76
	v_lshl_add_u32 v69, v71, 7, v76
	s_add_u32 s98, s20, s38
	s_addc_u32 s99, s21, s39
	global_load_dwordx4 v[80:83], v68, s[4:5]
	global_load_dwordx4 v[76:79], v69, s[4:5]
	global_load_dword v160, v155, s[26:27]
	s_nop 0
	global_load_dwordx2 v[240:241], v243, s[98:99]
	s_nop 0
	global_load_dwordx4 v[104:107], v[104:105], off
	s_nop 0
	v_mov_b32_e32 v153, 0
	v_dot4c_i32_i8_e32 v153, v64, v0
	v_mov_b32_e32 v64, 0
	v_dot4c_i32_i8_e32 v64, v60, v0
	v_dot4c_i32_i8_e32 v64, v61, v1
	v_dot4c_i32_i8_e32 v64, v62, v2
	v_dot4c_i32_i8_e32 v64, v63, v3
	v_dot4c_i32_i8_e32 v153, v65, v1
	v_dot4c_i32_i8_e32 v153, v66, v2
	v_dot4c_i32_i8_e32 v153, v67, v3
	v_add_u32_dpp v60, v64, v64 quad_perm:[1,0,3,2] row_mask:0xf bank_mask:0xf bound_ctrl:1
	v_mov_b32_e32 v64, 0
	v_dot4c_i32_i8_e32 v64, v56, v0
	v_mov_b32_e32 v56, 0
	v_dot4c_i32_i8_e32 v56, v52, v0
	v_dot4c_i32_i8_e32 v56, v53, v1
	v_dot4c_i32_i8_e32 v56, v54, v2
	v_dot4c_i32_i8_e32 v56, v55, v3
	v_dot4c_i32_i8_e32 v64, v57, v1
	v_dot4c_i32_i8_e32 v64, v58, v2
	v_dot4c_i32_i8_e32 v64, v59, v3
	v_add_u32_dpp v52, v56, v56 quad_perm:[1,0,3,2] row_mask:0xf bank_mask:0xf bound_ctrl:1
	v_mov_b32_e32 v56, 0
	v_dot4c_i32_i8_e32 v56, v48, v0
	v_mov_b32_e32 v48, 0
	v_dot4c_i32_i8_e32 v48, v44, v0
	v_dot4c_i32_i8_e32 v48, v45, v1
	v_dot4c_i32_i8_e32 v48, v46, v2
	v_dot4c_i32_i8_e32 v48, v47, v3
	v_dot4c_i32_i8_e32 v56, v49, v1
	v_dot4c_i32_i8_e32 v56, v50, v2
	v_dot4c_i32_i8_e32 v56, v51, v3
	v_add_u32_dpp v44, v48, v48 quad_perm:[1,0,3,2] row_mask:0xf bank_mask:0xf bound_ctrl:1
	v_mov_b32_e32 v48, 0
	v_dot4c_i32_i8_e32 v48, v40, v0
	v_mov_b32_e32 v40, 0
	v_dot4c_i32_i8_e32 v40, v36, v0
	v_dot4c_i32_i8_e32 v40, v37, v1
	v_dot4c_i32_i8_e32 v40, v38, v2
	v_dot4c_i32_i8_e32 v40, v39, v3
	v_dot4c_i32_i8_e32 v48, v41, v1
	v_dot4c_i32_i8_e32 v48, v42, v2
	v_dot4c_i32_i8_e32 v48, v43, v3
	v_add_u32_dpp v36, v40, v40 quad_perm:[1,0,3,2] row_mask:0xf bank_mask:0xf bound_ctrl:1
	v_mov_b32_e32 v40, 0
	v_dot4c_i32_i8_e32 v40, v32, v0
	v_mov_b32_e32 v32, 0
	v_dot4c_i32_i8_e32 v32, v28, v0
	v_dot4c_i32_i8_e32 v32, v29, v1
	v_dot4c_i32_i8_e32 v32, v30, v2
	v_dot4c_i32_i8_e32 v32, v31, v3
	v_dot4c_i32_i8_e32 v40, v33, v1
	v_dot4c_i32_i8_e32 v40, v34, v2
	v_dot4c_i32_i8_e32 v40, v35, v3
	v_add_u32_dpp v28, v32, v32 quad_perm:[1,0,3,2] row_mask:0xf bank_mask:0xf bound_ctrl:1
	v_mov_b32_e32 v32, 0
	v_dot4c_i32_i8_e32 v32, v24, v0
	v_mov_b32_e32 v24, 0
	v_dot4c_i32_i8_e32 v24, v20, v0
	v_dot4c_i32_i8_e32 v24, v21, v1
	v_dot4c_i32_i8_e32 v24, v22, v2
	v_dot4c_i32_i8_e32 v24, v23, v3
	v_dot4c_i32_i8_e32 v32, v25, v1
	v_dot4c_i32_i8_e32 v32, v26, v2
	v_dot4c_i32_i8_e32 v32, v27, v3
	v_add_u32_dpp v20, v24, v24 quad_perm:[1,0,3,2] row_mask:0xf bank_mask:0xf bound_ctrl:1
	v_mov_b32_e32 v24, 0
	v_dot4c_i32_i8_e32 v24, v16, v0
	v_mov_b32_e32 v16, 0
	v_dot4c_i32_i8_e32 v16, v12, v0
	v_dot4c_i32_i8_e32 v16, v13, v1
	v_dot4c_i32_i8_e32 v16, v14, v2
	v_dot4c_i32_i8_e32 v16, v15, v3
	v_dot4c_i32_i8_e32 v24, v17, v1
	v_dot4c_i32_i8_e32 v24, v18, v2
	v_dot4c_i32_i8_e32 v24, v19, v3
	v_add_u32_dpp v12, v16, v16 quad_perm:[1,0,3,2] row_mask:0xf bank_mask:0xf bound_ctrl:1
	v_mov_b32_e32 v16, 0
	v_dot4c_i32_i8_e32 v16, v4, v0
	v_mov_b32_e32 v4, 0
	v_dot4c_i32_i8_e32 v4, v8, v0
	v_dot4c_i32_i8_e32 v16, v5, v1
	v_dot4c_i32_i8_e32 v4, v9, v1
	v_dot4c_i32_i8_e32 v16, v6, v2
	v_dot4c_i32_i8_e32 v4, v10, v2
	v_dot4c_i32_i8_e32 v16, v7, v3
	v_dot4c_i32_i8_e32 v4, v11, v3
	v_add_u32_dpp v61, v153, v153 quad_perm:[1,0,3,2] row_mask:0xf bank_mask:0xf bound_ctrl:1
	v_add_u32_dpp v53, v64, v64 quad_perm:[1,0,3,2] row_mask:0xf bank_mask:0xf bound_ctrl:1
	v_add_u32_dpp v45, v56, v56 quad_perm:[1,0,3,2] row_mask:0xf bank_mask:0xf bound_ctrl:1
	v_add_u32_dpp v37, v48, v48 quad_perm:[1,0,3,2] row_mask:0xf bank_mask:0xf bound_ctrl:1
	v_add_u32_dpp v29, v40, v40 quad_perm:[1,0,3,2] row_mask:0xf bank_mask:0xf bound_ctrl:1
	v_add_u32_dpp v21, v32, v32 quad_perm:[1,0,3,2] row_mask:0xf bank_mask:0xf bound_ctrl:1
	v_add_u32_dpp v13, v24, v24 quad_perm:[1,0,3,2] row_mask:0xf bank_mask:0xf bound_ctrl:1
	v_add_u32_dpp v0, v4, v4 quad_perm:[1,0,3,2] row_mask:0xf bank_mask:0xf bound_ctrl:1
	v_add_u32_dpp v1, v16, v16 quad_perm:[1,0,3,2] row_mask:0xf bank_mask:0xf bound_ctrl:1
	v_add_u32_dpp v60, v60, v60 quad_perm:[2,3,0,1] row_mask:0xf bank_mask:0xf bound_ctrl:1
	v_add_u32_dpp v61, v61, v61 quad_perm:[2,3,0,1] row_mask:0xf bank_mask:0xf bound_ctrl:1
	v_add_u32_dpp v52, v52, v52 quad_perm:[2,3,0,1] row_mask:0xf bank_mask:0xf bound_ctrl:1
	v_add_u32_dpp v53, v53, v53 quad_perm:[2,3,0,1] row_mask:0xf bank_mask:0xf bound_ctrl:1
	v_add_u32_dpp v44, v44, v44 quad_perm:[2,3,0,1] row_mask:0xf bank_mask:0xf bound_ctrl:1
	v_add_u32_dpp v46, v45, v45 quad_perm:[2,3,0,1] row_mask:0xf bank_mask:0xf bound_ctrl:1
	v_add_u32_dpp v36, v36, v36 quad_perm:[2,3,0,1] row_mask:0xf bank_mask:0xf bound_ctrl:1
	v_add_u32_dpp v37, v37, v37 quad_perm:[2,3,0,1] row_mask:0xf bank_mask:0xf bound_ctrl:1
	v_add_u32_dpp v28, v28, v28 quad_perm:[2,3,0,1] row_mask:0xf bank_mask:0xf bound_ctrl:1
	v_add_u32_dpp v29, v29, v29 quad_perm:[2,3,0,1] row_mask:0xf bank_mask:0xf bound_ctrl:1
	v_add_u32_dpp v20, v20, v20 quad_perm:[2,3,0,1] row_mask:0xf bank_mask:0xf bound_ctrl:1
	v_add_u32_dpp v21, v21, v21 quad_perm:[2,3,0,1] row_mask:0xf bank_mask:0xf bound_ctrl:1
	v_add_u32_dpp v12, v12, v12 quad_perm:[2,3,0,1] row_mask:0xf bank_mask:0xf bound_ctrl:1
	v_add_u32_dpp v13, v13, v13 quad_perm:[2,3,0,1] row_mask:0xf bank_mask:0xf bound_ctrl:1
	v_add_u32_dpp v0, v0, v0 quad_perm:[2,3,0,1] row_mask:0xf bank_mask:0xf bound_ctrl:1
	v_add_u32_dpp v1, v1, v1 quad_perm:[2,3,0,1] row_mask:0xf bank_mask:0xf bound_ctrl:1
	v_mov_b32_dpp v62, v61 row_half_mirror row_mask:0xf bank_mask:0xf bound_ctrl:1
	v_mov_b32_dpp v63, v60 row_half_mirror row_mask:0xf bank_mask:0xf bound_ctrl:1
	v_mov_b32_dpp v54, v53 row_half_mirror row_mask:0xf bank_mask:0xf bound_ctrl:1
	v_mov_b32_dpp v55, v52 row_half_mirror row_mask:0xf bank_mask:0xf bound_ctrl:1
	v_mov_b32_dpp v47, v46 row_half_mirror row_mask:0xf bank_mask:0xf bound_ctrl:1
	v_mov_b32_dpp v45, v44 row_half_mirror row_mask:0xf bank_mask:0xf bound_ctrl:1
	v_mov_b32_dpp v38, v37 row_half_mirror row_mask:0xf bank_mask:0xf bound_ctrl:1
	v_mov_b32_dpp v39, v36 row_half_mirror row_mask:0xf bank_mask:0xf bound_ctrl:1
	v_mov_b32_dpp v30, v29 row_half_mirror row_mask:0xf bank_mask:0xf bound_ctrl:1
	v_mov_b32_dpp v31, v28 row_half_mirror row_mask:0xf bank_mask:0xf bound_ctrl:1
	v_mov_b32_dpp v22, v21 row_half_mirror row_mask:0xf bank_mask:0xf bound_ctrl:1
	v_mov_b32_dpp v23, v20 row_half_mirror row_mask:0xf bank_mask:0xf bound_ctrl:1
	v_mov_b32_dpp v14, v13 row_half_mirror row_mask:0xf bank_mask:0xf bound_ctrl:1
	v_mov_b32_dpp v15, v12 row_half_mirror row_mask:0xf bank_mask:0xf bound_ctrl:1
	v_mov_b32_dpp v2, v1 row_half_mirror row_mask:0xf bank_mask:0xf bound_ctrl:1
	v_mov_b32_dpp v3, v0 row_half_mirror row_mask:0xf bank_mask:0xf bound_ctrl:1
	s_and_saveexec_b64 s[26:27], s[2:3]
	s_cbranch_execz .LBB0_538
	v_add_u32_e32 v10, v1, v2
	v_add_u32_e32 v11, v0, v3
	v_add_u32_e32 v2, v53, v54
	v_add_u32_e32 v3, v52, v55
	v_add_u32_e32 v0, v61, v62
	v_add_u32_e32 v1, v60, v63
	v_add_u32_e32 v6, v37, v38
	v_add_u32_e32 v7, v36, v39
	v_add_u32_e32 v4, v46, v47
	v_cvt_f32_i32_e32 v1, v1
	v_cvt_f32_i32_e32 v0, v0
	v_cvt_f32_i32_e32 v3, v3
	v_cvt_f32_i32_e32 v2, v2
	v_add_u32_e32 v5, v44, v45
	v_cvt_f32_i32_e32 v5, v5
	v_cvt_f32_i32_e32 v4, v4
	v_cvt_f32_i32_e32 v7, v7
	v_cvt_f32_i32_e32 v6, v6
	v_add_u32_e32 v13, v13, v14
	v_add_u32_e32 v12, v12, v15
	v_add_u32_e32 v8, v21, v22
	v_add_u32_e32 v9, v20, v23
	v_add_u32_e32 v14, v29, v30
	v_add_u32_e32 v15, v28, v31
	v_pk_mul_f32 v[0:1], v[158:159], v[0:1] op_sel_hi:[0,1]
	v_pk_mul_f32 v[2:3], v[158:159], v[2:3] op_sel_hi:[0,1]
	v_cvt_pk_f16_f32 v0, v0, v1
	v_cvt_pk_f16_f32 v1, v2, v3
	v_pk_mul_f32 v[2:3], v[158:159], v[4:5] op_sel_hi:[0,1]
	v_pk_mul_f32 v[4:5], v[158:159], v[6:7] op_sel_hi:[0,1]
	v_cvt_f32_i32_e32 v7, v15
	v_cvt_f32_i32_e32 v6, v14
	v_cvt_f32_i32_e32 v9, v9
	v_cvt_f32_i32_e32 v8, v8
	v_cvt_pk_f16_f32 v2, v2, v3
	v_cvt_pk_f16_f32 v3, v4, v5
	v_pk_mul_f32 v[4:5], v[158:159], v[6:7] op_sel_hi:[0,1]
	v_pk_mul_f32 v[6:7], v[158:159], v[8:9] op_sel_hi:[0,1]
	v_cvt_f32_i32_e32 v9, v12
	v_cvt_f32_i32_e32 v8, v13
	v_cvt_f32_i32_e32 v11, v11
	v_cvt_f32_i32_e32 v10, v10
	s_ashr_i32 s23, s22, 31
	s_ashr_i32 s17, s16, 31
	s_lshl_b64 s[22:23], s[22:23], 22
	s_add_u32 s9, s14, s22
	s_addc_u32 s11, s15, s23
	s_lshl_b64 s[16:17], s[16:17], 8
	v_cvt_pk_f16_f32 v4, v4, v5
	v_cvt_pk_f16_f32 v5, v6, v7
	v_pk_mul_f32 v[6:7], v[158:159], v[8:9] op_sel_hi:[0,1]
	v_pk_mul_f32 v[8:9], v[158:159], v[10:11] op_sel_hi:[0,1]
	s_add_u32 s16, s9, s16
	v_cvt_pk_f16_f32 v6, v6, v7
	v_cvt_pk_f16_f32 v7, v8, v9
	s_addc_u32 s17, s11, s17
	v_lshlrev_b32_e32 v8, 1, v152
	global_store_dwordx4 v8, v[0:3], s[16:17]
	global_store_dwordx4 v8, v[4:7], s[16:17] offset:16
.LBB0_538:
	s_or_b64 exec, exec, s[26:27]
	s_cmp_gt_i32 s10, 7
	s_cbranch_scc1 .LBB0_541
	s_add_i32 s9, s19, s36
	s_cmpk_gt_i32 s9, 0x3fff
	s_cselect_b32 s23, s6, s9
	s_cselect_b32 s9, s33, 0
	s_add_i32 s22, s9, s7
	s_and_b64 s[16:17], s[24:25], exec
	s_cselect_b32 s24, s19, s8
	s_cselect_b32 s16, s7, s10
	s_ashr_i32 s25, s24, 31
	s_lshl_b64 s[26:27], s[24:25], 10
	s_add_u32 s9, s28, s26
	s_addc_u32 s11, s29, s27
	s_lshl_b32 s17, s16, 7
	s_ashr_i32 s27, s17, 31
	s_add_u32 s26, s9, s17
	v_lshl_or_b32 v0, s16, 21, v154
	s_addc_u32 s27, s11, s27
	s_ashr_i32 s17, s16, 31
	s_lshl_b64 s[24:25], s[24:25], 5
	s_waitcnt vmcnt(2)
	ds_swizzle_b32 v108, v240 offset:24
	ds_swizzle_b32 v109, v241 offset:24
	ds_swizzle_b32 v110, v240 offset:56
	ds_swizzle_b32 v111, v241 offset:56
	ds_swizzle_b32 v92, v240 offset:88
	ds_swizzle_b32 v93, v241 offset:88
	ds_swizzle_b32 v94, v240 offset:120
	ds_swizzle_b32 v95, v241 offset:120
	ds_swizzle_b32 v72, v240 offset:152
	ds_swizzle_b32 v73, v241 offset:152
	ds_swizzle_b32 v74, v240 offset:184
	ds_swizzle_b32 v75, v241 offset:184
	ds_swizzle_b32 v68, v240 offset:216
	ds_swizzle_b32 v69, v241 offset:216
	ds_swizzle_b32 v70, v240 offset:248
	ds_swizzle_b32 v71, v241 offset:248
	s_waitcnt lgkmcnt(0)
	s_nop 0
	v_lshl_add_u32 v1, v108, 7, v0
	s_add_u32 s9, s30, s24
	v_lshl_add_u32 v2, v109, 7, v0
	global_load_dwordx4 v[64:67], v1, s[4:5]
	global_load_dwordx4 v[60:63], v2, s[4:5]
	v_lshl_add_u32 v1, v110, 7, v0
	s_addc_u32 s11, s31, s25
	s_lshl_b64 s[16:17], s[16:17], 2
	v_lshl_add_u32 v2, v111, 7, v0
	global_load_dwordx4 v[56:59], v1, s[4:5]
	global_load_dwordx4 v[52:55], v2, s[4:5]
	v_lshl_add_u32 v1, v92, 7, v0
	s_add_u32 s16, s9, s16
	v_lshl_add_u32 v2, v93, 7, v0
	global_load_dwordx4 v[48:51], v1, s[4:5]
	global_load_dwordx4 v[44:47], v2, s[4:5]
	v_lshl_add_u32 v1, v94, 7, v0
	s_addc_u32 s17, s11, s17
	v_lshl_add_u32 v2, v95, 7, v0
	global_load_dwordx4 v[40:43], v1, s[4:5]
	global_load_dwordx4 v[36:39], v2, s[4:5]
	v_lshl_add_u32 v1, v72, 7, v0
	s_cmp_lt_i32 s22, 8
	v_lshl_add_u32 v2, v73, 7, v0
	global_load_dwordx4 v[32:35], v1, s[4:5]
	global_load_dwordx4 v[28:31], v2, s[4:5]
	v_lshl_add_u32 v1, v74, 7, v0
	s_cselect_b32 s24, s23, s8
	v_lshl_add_u32 v2, v75, 7, v0
	global_load_dwordx4 v[24:27], v1, s[4:5]
	global_load_dwordx4 v[20:23], v2, s[4:5]
	v_lshl_add_u32 v1, v68, 7, v0
	s_ashr_i32 s25, s24, 31
	v_lshl_add_u32 v2, v69, 7, v0
	global_load_dwordx4 v[16:19], v1, s[4:5]
	global_load_dwordx4 v[12:15], v2, s[4:5]
	v_lshl_add_u32 v1, v70, 7, v0
	v_lshl_add_u32 v0, v71, 7, v0
	s_lshl_b64 s[24:25], s[24:25], 9
	global_load_dwordx4 v[4:7], v1, s[4:5]
	global_load_dwordx4 v[8:11], v0, s[4:5]
	v_lshl_add_u64 v[0:1], s[26:27], 0, v[154:155]
	s_add_u32 s98, s20, s24
	s_addc_u32 s99, s21, s25
	global_load_dword v158, v155, s[16:17]
	global_load_dwordx2 v[240:241], v243, s[98:99]
	s_nop 0
	global_load_dwordx4 v[0:3], v[0:1], off
	s_nop 0
	v_mov_b32_e32 v153, 0
	v_dot4c_i32_i8_e32 v153, v148, v104
	v_mov_b32_e32 v148, 0
	v_dot4c_i32_i8_e32 v148, v144, v104
	v_dot4c_i32_i8_e32 v148, v145, v105
	v_dot4c_i32_i8_e32 v148, v146, v106
	v_dot4c_i32_i8_e32 v148, v147, v107
	v_dot4c_i32_i8_e32 v153, v149, v105
	v_dot4c_i32_i8_e32 v153, v150, v106
	v_dot4c_i32_i8_e32 v153, v151, v107
	v_add_u32_dpp v144, v148, v148 quad_perm:[1,0,3,2] row_mask:0xf bank_mask:0xf bound_ctrl:1
	v_mov_b32_e32 v148, 0
	v_dot4c_i32_i8_e32 v148, v140, v104
	v_mov_b32_e32 v140, 0
	v_dot4c_i32_i8_e32 v140, v136, v104
	v_dot4c_i32_i8_e32 v140, v137, v105
	v_dot4c_i32_i8_e32 v140, v138, v106
	v_dot4c_i32_i8_e32 v140, v139, v107
	v_dot4c_i32_i8_e32 v148, v141, v105
	v_dot4c_i32_i8_e32 v148, v142, v106
	v_dot4c_i32_i8_e32 v148, v143, v107
	v_add_u32_dpp v136, v140, v140 quad_perm:[1,0,3,2] row_mask:0xf bank_mask:0xf bound_ctrl:1
	v_mov_b32_e32 v140, 0
	v_dot4c_i32_i8_e32 v140, v132, v104
	v_mov_b32_e32 v132, 0
	v_dot4c_i32_i8_e32 v132, v128, v104
	v_dot4c_i32_i8_e32 v132, v129, v105
	v_dot4c_i32_i8_e32 v132, v130, v106
	v_dot4c_i32_i8_e32 v132, v131, v107
	v_dot4c_i32_i8_e32 v140, v133, v105
	v_dot4c_i32_i8_e32 v140, v134, v106
	v_dot4c_i32_i8_e32 v140, v135, v107
	v_add_u32_dpp v128, v132, v132 quad_perm:[1,0,3,2] row_mask:0xf bank_mask:0xf bound_ctrl:1
	v_mov_b32_e32 v132, 0
	v_dot4c_i32_i8_e32 v132, v124, v104
	v_mov_b32_e32 v124, 0
	v_dot4c_i32_i8_e32 v124, v120, v104
	v_dot4c_i32_i8_e32 v124, v121, v105
	v_dot4c_i32_i8_e32 v124, v122, v106
	v_dot4c_i32_i8_e32 v124, v123, v107
	v_dot4c_i32_i8_e32 v132, v125, v105
	v_dot4c_i32_i8_e32 v132, v126, v106
	v_dot4c_i32_i8_e32 v132, v127, v107
	v_add_u32_dpp v120, v124, v124 quad_perm:[1,0,3,2] row_mask:0xf bank_mask:0xf bound_ctrl:1
	v_mov_b32_e32 v124, 0
	v_dot4c_i32_i8_e32 v124, v116, v104
	v_mov_b32_e32 v116, 0
	v_dot4c_i32_i8_e32 v116, v112, v104
	v_dot4c_i32_i8_e32 v116, v113, v105
	v_dot4c_i32_i8_e32 v116, v114, v106
	v_dot4c_i32_i8_e32 v116, v115, v107
	v_dot4c_i32_i8_e32 v124, v117, v105
	v_dot4c_i32_i8_e32 v124, v118, v106
	v_dot4c_i32_i8_e32 v124, v119, v107
	v_add_u32_dpp v112, v116, v116 quad_perm:[1,0,3,2] row_mask:0xf bank_mask:0xf bound_ctrl:1
	v_mov_b32_e32 v116, 0
	v_dot4c_i32_i8_e32 v116, v100, v104
	v_mov_b32_e32 v100, 0
	v_dot4c_i32_i8_e32 v100, v96, v104
	v_dot4c_i32_i8_e32 v100, v97, v105
	v_dot4c_i32_i8_e32 v100, v98, v106
	v_dot4c_i32_i8_e32 v100, v99, v107
	v_dot4c_i32_i8_e32 v116, v101, v105
	v_dot4c_i32_i8_e32 v116, v102, v106
	v_dot4c_i32_i8_e32 v116, v103, v107
	v_add_u32_dpp v96, v100, v100 quad_perm:[1,0,3,2] row_mask:0xf bank_mask:0xf bound_ctrl:1
	v_mov_b32_e32 v100, 0
	v_dot4c_i32_i8_e32 v100, v88, v104
	v_mov_b32_e32 v88, 0
	v_dot4c_i32_i8_e32 v88, v84, v104
	v_dot4c_i32_i8_e32 v88, v85, v105
	v_dot4c_i32_i8_e32 v88, v86, v106
	v_dot4c_i32_i8_e32 v88, v87, v107
	v_dot4c_i32_i8_e32 v100, v89, v105
	v_dot4c_i32_i8_e32 v100, v90, v106
	v_dot4c_i32_i8_e32 v100, v91, v107
	v_add_u32_dpp v84, v88, v88 quad_perm:[1,0,3,2] row_mask:0xf bank_mask:0xf bound_ctrl:1
	v_mov_b32_e32 v88, 0
	v_dot4c_i32_i8_e32 v88, v80, v104
	v_mov_b32_e32 v80, 0
	v_dot4c_i32_i8_e32 v80, v76, v104
	v_dot4c_i32_i8_e32 v88, v81, v105
	v_dot4c_i32_i8_e32 v80, v77, v105
	v_dot4c_i32_i8_e32 v88, v82, v106
	v_dot4c_i32_i8_e32 v80, v78, v106
	v_dot4c_i32_i8_e32 v88, v83, v107
	v_dot4c_i32_i8_e32 v80, v79, v107
	v_add_u32_dpp v145, v153, v153 quad_perm:[1,0,3,2] row_mask:0xf bank_mask:0xf bound_ctrl:1
	v_add_u32_dpp v137, v148, v148 quad_perm:[1,0,3,2] row_mask:0xf bank_mask:0xf bound_ctrl:1
	v_add_u32_dpp v129, v140, v140 quad_perm:[1,0,3,2] row_mask:0xf bank_mask:0xf bound_ctrl:1
	v_add_u32_dpp v121, v132, v132 quad_perm:[1,0,3,2] row_mask:0xf bank_mask:0xf bound_ctrl:1
	v_add_u32_dpp v113, v124, v124 quad_perm:[1,0,3,2] row_mask:0xf bank_mask:0xf bound_ctrl:1
	v_add_u32_dpp v97, v116, v116 quad_perm:[1,0,3,2] row_mask:0xf bank_mask:0xf bound_ctrl:1
	v_add_u32_dpp v85, v100, v100 quad_perm:[1,0,3,2] row_mask:0xf bank_mask:0xf bound_ctrl:1
	v_add_u32_dpp v76, v80, v80 quad_perm:[1,0,3,2] row_mask:0xf bank_mask:0xf bound_ctrl:1
	v_add_u32_dpp v77, v88, v88 quad_perm:[1,0,3,2] row_mask:0xf bank_mask:0xf bound_ctrl:1
	v_add_u32_dpp v144, v144, v144 quad_perm:[2,3,0,1] row_mask:0xf bank_mask:0xf bound_ctrl:1
	v_add_u32_dpp v145, v145, v145 quad_perm:[2,3,0,1] row_mask:0xf bank_mask:0xf bound_ctrl:1
	v_add_u32_dpp v136, v136, v136 quad_perm:[2,3,0,1] row_mask:0xf bank_mask:0xf bound_ctrl:1
	v_add_u32_dpp v137, v137, v137 quad_perm:[2,3,0,1] row_mask:0xf bank_mask:0xf bound_ctrl:1
	v_add_u32_dpp v128, v128, v128 quad_perm:[2,3,0,1] row_mask:0xf bank_mask:0xf bound_ctrl:1
	v_add_u32_dpp v130, v129, v129 quad_perm:[2,3,0,1] row_mask:0xf bank_mask:0xf bound_ctrl:1
	v_add_u32_dpp v120, v120, v120 quad_perm:[2,3,0,1] row_mask:0xf bank_mask:0xf bound_ctrl:1
	v_add_u32_dpp v121, v121, v121 quad_perm:[2,3,0,1] row_mask:0xf bank_mask:0xf bound_ctrl:1
	v_add_u32_dpp v112, v112, v112 quad_perm:[2,3,0,1] row_mask:0xf bank_mask:0xf bound_ctrl:1
	v_add_u32_dpp v113, v113, v113 quad_perm:[2,3,0,1] row_mask:0xf bank_mask:0xf bound_ctrl:1
	v_add_u32_dpp v96, v96, v96 quad_perm:[2,3,0,1] row_mask:0xf bank_mask:0xf bound_ctrl:1
	v_add_u32_dpp v97, v97, v97 quad_perm:[2,3,0,1] row_mask:0xf bank_mask:0xf bound_ctrl:1
	v_add_u32_dpp v84, v84, v84 quad_perm:[2,3,0,1] row_mask:0xf bank_mask:0xf bound_ctrl:1
	v_add_u32_dpp v85, v85, v85 quad_perm:[2,3,0,1] row_mask:0xf bank_mask:0xf bound_ctrl:1
	v_add_u32_dpp v76, v76, v76 quad_perm:[2,3,0,1] row_mask:0xf bank_mask:0xf bound_ctrl:1
	v_add_u32_dpp v77, v77, v77 quad_perm:[2,3,0,1] row_mask:0xf bank_mask:0xf bound_ctrl:1
	v_mov_b32_dpp v146, v145 row_half_mirror row_mask:0xf bank_mask:0xf bound_ctrl:1
	v_mov_b32_dpp v147, v144 row_half_mirror row_mask:0xf bank_mask:0xf bound_ctrl:1
	v_mov_b32_dpp v138, v137 row_half_mirror row_mask:0xf bank_mask:0xf bound_ctrl:1
	v_mov_b32_dpp v139, v136 row_half_mirror row_mask:0xf bank_mask:0xf bound_ctrl:1
	v_mov_b32_dpp v131, v130 row_half_mirror row_mask:0xf bank_mask:0xf bound_ctrl:1
	v_mov_b32_dpp v129, v128 row_half_mirror row_mask:0xf bank_mask:0xf bound_ctrl:1
	v_mov_b32_dpp v122, v121 row_half_mirror row_mask:0xf bank_mask:0xf bound_ctrl:1
	v_mov_b32_dpp v123, v120 row_half_mirror row_mask:0xf bank_mask:0xf bound_ctrl:1
	v_mov_b32_dpp v114, v113 row_half_mirror row_mask:0xf bank_mask:0xf bound_ctrl:1
	v_mov_b32_dpp v115, v112 row_half_mirror row_mask:0xf bank_mask:0xf bound_ctrl:1
	v_mov_b32_dpp v98, v97 row_half_mirror row_mask:0xf bank_mask:0xf bound_ctrl:1
	v_mov_b32_dpp v99, v96 row_half_mirror row_mask:0xf bank_mask:0xf bound_ctrl:1
	v_mov_b32_dpp v86, v85 row_half_mirror row_mask:0xf bank_mask:0xf bound_ctrl:1
	v_mov_b32_dpp v87, v84 row_half_mirror row_mask:0xf bank_mask:0xf bound_ctrl:1
	v_mov_b32_dpp v78, v77 row_half_mirror row_mask:0xf bank_mask:0xf bound_ctrl:1
	v_mov_b32_dpp v79, v76 row_half_mirror row_mask:0xf bank_mask:0xf bound_ctrl:1
	s_and_saveexec_b64 s[16:17], s[2:3]
	s_cbranch_execz .LBB0_534
	v_add_u32_e32 v88, v77, v78
	v_add_u32_e32 v89, v76, v79
	v_add_u32_e32 v78, v137, v138
	v_add_u32_e32 v79, v136, v139
	v_add_u32_e32 v76, v145, v146
	v_add_u32_e32 v77, v144, v147
	v_add_u32_e32 v82, v121, v122
	v_add_u32_e32 v83, v120, v123
	v_add_u32_e32 v80, v130, v131
	v_cvt_f32_i32_e32 v77, v77
	v_cvt_f32_i32_e32 v76, v76
	v_cvt_f32_i32_e32 v79, v79
	v_cvt_f32_i32_e32 v78, v78
	v_add_u32_e32 v81, v128, v129
	v_cvt_f32_i32_e32 v81, v81
	v_cvt_f32_i32_e32 v80, v80
	v_cvt_f32_i32_e32 v83, v83
	v_cvt_f32_i32_e32 v82, v82
	v_add_u32_e32 v86, v85, v86
	v_add_u32_e32 v87, v84, v87
	v_add_u32_e32 v84, v97, v98
	v_add_u32_e32 v85, v96, v99
	v_add_u32_e32 v90, v113, v114
	v_add_u32_e32 v91, v112, v115
	v_pk_mul_f32 v[76:77], v[160:161], v[76:77] op_sel_hi:[0,1]
	v_pk_mul_f32 v[78:79], v[160:161], v[78:79] op_sel_hi:[0,1]
	v_cvt_pk_f16_f32 v76, v76, v77
	v_cvt_pk_f16_f32 v77, v78, v79
	v_pk_mul_f32 v[78:79], v[160:161], v[80:81] op_sel_hi:[0,1]
	v_pk_mul_f32 v[80:81], v[160:161], v[82:83] op_sel_hi:[0,1]
	v_cvt_f32_i32_e32 v83, v91
	v_cvt_f32_i32_e32 v82, v90
	v_cvt_f32_i32_e32 v85, v85
	v_cvt_f32_i32_e32 v84, v84
	v_cvt_pk_f16_f32 v78, v78, v79
	v_cvt_pk_f16_f32 v79, v80, v81
	v_pk_mul_f32 v[80:81], v[160:161], v[82:83] op_sel_hi:[0,1]
	v_pk_mul_f32 v[82:83], v[160:161], v[84:85] op_sel_hi:[0,1]
	v_cvt_f32_i32_e32 v85, v87
	v_cvt_f32_i32_e32 v84, v86
	v_cvt_f32_i32_e32 v87, v89
	v_cvt_f32_i32_e32 v86, v88
	s_ashr_i32 s11, s10, 31
	s_ashr_i32 s9, s8, 31
	s_lshl_b64 s[10:11], s[10:11], 22
	s_add_u32 s10, s14, s10
	s_addc_u32 s11, s15, s11
	s_lshl_b64 s[8:9], s[8:9], 8
	v_cvt_pk_f16_f32 v80, v80, v81
	v_cvt_pk_f16_f32 v81, v82, v83
	v_pk_mul_f32 v[82:83], v[160:161], v[84:85] op_sel_hi:[0,1]
	v_pk_mul_f32 v[84:85], v[160:161], v[86:87] op_sel_hi:[0,1]
	s_add_u32 s8, s10, s8
	v_cvt_pk_f16_f32 v82, v82, v83
	v_cvt_pk_f16_f32 v83, v84, v85
	s_addc_u32 s9, s11, s9
	v_lshlrev_b32_e32 v84, 1, v152
	global_store_dwordx4 v84, v[76:79], s[8:9]
	global_store_dwordx4 v84, v[80:83], s[8:9] offset:16
	s_branch .LBB0_534

; #define PV_LOAD_A(ID, tt) { _Pragma("unroll") for (int i = 0; i < 4; ++i) ID[i] = *(const int4*)(selE + (size_t)(tt) * 128 + sub * 16 + 4 * i); }
; __device__ void phase_pv(const Params& p, const XcdBarrier& xb) {
;     ...
;   int4 id_n[4], id_nn[4];
;   int s_c = xi, t_c = wrank;
;   int s_n = s_c, t_n = t_c + nw; if (t_n >= T) { t_n = wrank; s_n += nx; }
;   int s_nn = s_n, t_nn = t_n + nw; if (t_nn >= T) { t_nn = wrank; s_nn += nx; }
;     ...
;   if (s_c < 8) {
;     {
;       int4 id_c[4];
;       PV_LOAD_A(id_c, t_c)
;       PV_LOAD_B(v0, cf0, hold0, id_c, s_c, t_c)
;     }
;     { const int tl_ = (s_n < 8) ? t_n : t_c; PV_LOAD_A(id_n, tl_) }
.LBB0_619:
	s_or_b64 exec, exec, s[2:3]
	v_mov_b32_e32 v80, v197
	s_barrier
	s_cmp_gt_i32 s18, 7
	v_readfirstlane_b32 s2, v80
	s_cbranch_scc1 .LBB0_624
	s_ashr_i32 s2, s2, 6
	s_add_u32 s4, s60, 0x3480000
	s_addc_u32 s5, s61, 0
	s_lshl_b32 s3, s91, 2
	s_add_i32 s6, s3, s2
	s_lshl_b32 s19, s90, 2
	s_add_i32 s2, s19, s6
	s_cmpk_gt_i32 s2, 0x3fff
	s_cselect_b32 s8, s6, s2
	s_cselect_b32 s2, s33, 0
	s_add_i32 s3, s8, s19
	s_add_i32 s22, s2, s18
	s_cmpk_gt_i32 s3, 0x3fff
	s_cselect_b32 s2, s33, 0
	s_cselect_b32 s26, s6, s3
	s_ashr_i32 s7, s6, 31
	s_add_i32 s27, s2, s22
	s_lshl_b64 s[2:3], s[6:7], 9
	s_add_u32 s16, s20, s2
	v_lshlrev_b32_e32 v0, 3, v80
	s_addc_u32 s17, s21, s3
	v_and_b32_e32 v194, 0x1c0, v0
	v_and_b32_e32 v252, 7, v197
	v_lshlrev_b32_e32 v252, 3, v252
	v_mov_b32_e32 v253, 0
	v_add_u32_e32 v254, v194, v252
	global_load_dwordx4 v[4:7], v194, s[16:17]
	global_load_dwordx4 v[8:11], v194, s[16:17] offset:16
	global_load_dwordx4 v[16:19], v194, s[16:17] offset:32
	global_load_dwordx4 v[20:23], v194, s[16:17] offset:48
	s_add_u32 s2, s10, s2
	s_addc_u32 s3, s11, s3
	v_lshlrev_b32_e32 v0, 4, v80
	s_cmp_lt_i32 s22, 8
	v_and_b32_e32 v196, 0x70, v0
	global_load_dwordx2 v[248:249], v254, s[2:3]
	s_cselect_b32 s2, s8, s6
	s_ashr_i32 s3, s2, 31
	s_lshl_b64 s[2:3], s[2:3], 9
	v_lshl_or_b32 v24, s18, 21, v196
	s_add_u32 s2, s20, s2
	s_addc_u32 s3, s21, s3
	global_load_dwordx2 v[250:251], v254, s[2:3]
	v_mov_b32_e32 v195, 0
	v_lshl_add_u64 v[198:199], s[10:11], 0, v[194:195]
	v_lshl_add_u64 v[200:201], s[20:21], 0, v[194:195]
	v_lshl_add_u64 v[244:245], v[198:199], 0, v[252:253]
	v_lshl_add_u64 v[246:247], v[200:201], 0, v[252:253]
	s_mov_b32 s10, 0x3b800000
	s_movk_i32 s7, 0x7fff
	s_mov_b32 s11, 0xffff0000
	v_mov_b32_e32 v205, v195
	v_mov_b32_e32 v208, 1
	s_mov_b32 s23, s6
	s_waitcnt vmcnt(5)
	v_lshl_add_u32 v82, v4, 7, v24
	s_waitcnt vmcnt(4)
	v_lshl_add_u32 v9, v9, 7, v24
	v_lshl_add_u32 v8, v8, 7, v24
	v_lshl_add_u32 v11, v11, 7, v24
	v_lshl_add_u32 v10, v10, 7, v24
	v_lshl_add_u32 v81, v5, 7, v24
	v_lshl_add_u32 v83, v7, 7, v24
	v_lshl_add_u32 v84, v6, 7, v24
	s_waitcnt vmcnt(3)
	v_lshl_add_u32 v85, v17, 7, v24
	v_lshl_add_u32 v86, v16, 7, v24
	v_lshl_add_u32 v87, v19, 7, v24
	v_lshl_add_u32 v88, v18, 7, v24
	s_waitcnt vmcnt(2)
	v_lshl_add_u32 v89, v21, 7, v24
	v_lshl_add_u32 v90, v20, 7, v24
	v_lshl_add_u32 v91, v23, 7, v24
	v_lshl_add_u32 v92, v22, 7, v24
	global_load_dwordx4 v[76:79], v82, s[4:5]
	global_load_dwordx4 v[72:75], v81, s[4:5]
	global_load_dwordx4 v[68:71], v84, s[4:5]
	global_load_dwordx4 v[64:67], v83, s[4:5]
	global_load_dwordx4 v[56:59], v8, s[4:5]
	global_load_dwordx4 v[52:55], v9, s[4:5]
	global_load_dwordx4 v[48:51], v10, s[4:5]
	global_load_dwordx4 v[44:47], v11, s[4:5]
	global_load_dwordx4 v[40:43], v86, s[4:5]
	global_load_dwordx4 v[32:35], v85, s[4:5]
	global_load_dwordx4 v[28:31], v88, s[4:5]
	global_load_dwordx4 v[24:27], v87, s[4:5]
	global_load_dwordx4 v[20:23], v90, s[4:5]
	global_load_dwordx4 v[16:19], v89, s[4:5]
	global_load_dwordx4 v[4:7], v92, s[4:5]
	global_load_dwordx4 v[8:11], v91, s[4:5]
	v_lshrrev_b32_e32 v81, 2, v80
	v_and_b32_e32 v82, 14, v81
	v_and_b32_e32 v80, 8, v80
	v_lshlrev_b32_e32 v202, 1, v82
	v_cmp_eq_u32_e64 s[2:3], 0, v80
	v_lshlrev_b32_e32 v194, 1, v196
	v_mov_b32_e32 v204, v202
	s_waitcnt vmcnt(0)
	s_nop 0
	s_branch .LBB0_622

.LBB0_622:
	s_mov_b32 s9, s18
	s_cmp_lt_i32 s22, 8
	s_cselect_b32 s17, s22, s9
	s_waitcnt vmcnt(1)
	ds_swizzle_b32 v140, v250 offset:24
	ds_swizzle_b32 v141, v251 offset:24
	ds_swizzle_b32 v142, v250 offset:56
	ds_swizzle_b32 v143, v251 offset:56
	ds_swizzle_b32 v132, v250 offset:88
	ds_swizzle_b32 v133, v251 offset:88
	ds_swizzle_b32 v134, v250 offset:120
	ds_swizzle_b32 v135, v251 offset:120
	ds_swizzle_b32 v108, v250 offset:152
	ds_swizzle_b32 v109, v251 offset:152
	ds_swizzle_b32 v110, v250 offset:184
	ds_swizzle_b32 v111, v251 offset:184
	ds_swizzle_b32 v100, v250 offset:216
	ds_swizzle_b32 v101, v251 offset:216
	ds_swizzle_b32 v102, v250 offset:248
	ds_swizzle_b32 v103, v251 offset:248
	ds_swizzle_b32 v60, v248 offset:24
	ds_swizzle_b32 v61, v249 offset:24
	ds_swizzle_b32 v62, v248 offset:56
	ds_swizzle_b32 v63, v249 offset:56
	ds_swizzle_b32 v36, v248 offset:88
	ds_swizzle_b32 v37, v249 offset:88
	ds_swizzle_b32 v38, v248 offset:120
	ds_swizzle_b32 v39, v249 offset:120
	ds_swizzle_b32 v12, v248 offset:152
	ds_swizzle_b32 v13, v249 offset:152
	ds_swizzle_b32 v14, v248 offset:184
	ds_swizzle_b32 v15, v249 offset:184
	ds_swizzle_b32 v0, v248 offset:216
	ds_swizzle_b32 v1, v249 offset:216
	ds_swizzle_b32 v2, v248 offset:248
	ds_swizzle_b32 v3, v249 offset:248
	s_waitcnt lgkmcnt(0)
	s_nop 0
	v_lshl_or_b32 v80, s17, 21, v196
	s_waitcnt vmcnt(1)
	v_lshl_add_u32 v81, v140, 7, v80
	v_lshl_add_u32 v82, v141, 7, v80
	s_mov_b32 s16, s23
	global_load_dwordx4 v[168:171], v81, s[4:5]
	global_load_dwordx4 v[164:167], v82, s[4:5]
	v_lshl_add_u32 v81, v142, 7, v80
	v_lshl_add_u32 v82, v143, 7, v80
	global_load_dwordx4 v[160:163], v81, s[4:5]
	global_load_dwordx4 v[156:159], v82, s[4:5]
	v_lshl_add_u32 v81, v132, 7, v80
	v_lshl_add_u32 v82, v133, 7, v80
	s_cselect_b32 s20, s8, s16
	global_load_dwordx4 v[152:155], v81, s[4:5]
	global_load_dwordx4 v[144:147], v82, s[4:5]
	v_lshl_add_u32 v81, v134, 7, v80
	v_lshl_add_u32 v82, v135, 7, v80
	s_ashr_i32 s21, s20, 31
	global_load_dwordx4 v[136:139], v81, s[4:5]
	global_load_dwordx4 v[128:131], v82, s[4:5]
	v_lshl_add_u32 v81, v108, 7, v80
	v_lshl_add_u32 v82, v109, 7, v80
	s_lshl_b64 s[20:21], s[20:21], 9
	global_load_dwordx4 v[124:127], v81, s[4:5]
	global_load_dwordx4 v[120:123], v82, s[4:5]
	v_lshl_add_u32 v81, v110, 7, v80
	v_lshl_add_u32 v82, v111, 7, v80
	s_cmp_lt_i32 s27, 8
	global_load_dwordx4 v[112:115], v81, s[4:5]
	global_load_dwordx4 v[104:107], v82, s[4:5]
	v_lshl_add_u32 v81, v100, 7, v80
	v_lshl_add_u32 v82, v101, 7, v80
	v_lshl_add_u64 v[100:101], v[244:245], 0, s[20:21]
	s_cselect_b64 s[20:21], -1, 0
	s_and_b64 s[24:25], s[20:21], exec
	s_cselect_b32 s24, s26, s16
	s_ashr_i32 s25, s24, 31
	global_load_dwordx4 v[96:99], v81, s[4:5]
	global_load_dwordx4 v[92:95], v82, s[4:5]
	v_lshl_add_u32 v81, v102, 7, v80
	v_lshl_add_u32 v80, v103, 7, v80
	s_lshl_b64 s[24:25], s[24:25], 9
	global_load_dwordx4 v[88:91], v81, s[4:5]
	s_nop 0
	global_load_dwordx4 v[80:83], v80, s[4:5]
	s_nop 0
	global_load_dwordx2 v[248:249], v[100:101], off
	v_lshl_add_u64 v[100:101], v[246:247], 0, s[24:25]
	global_load_dwordx2 v[250:251], v[100:101], off
	v_cvt_scalef32_pk_f16_fp8 v100, v76, 1.0
	v_cvt_scalef32_pk_f16_fp8 v76, v76, 1.0 op_sel:[1,0,0]
	v_cvt_scalef32_pk_f16_fp8 v101, v77, 1.0
	v_cvt_scalef32_pk_f16_fp8 v77, v77, 1.0 op_sel:[1,0,0]
	v_cvt_scalef32_pk_f16_fp8 v102, v78, 1.0
	v_cvt_scalef32_pk_f16_fp8 v78, v78, 1.0 op_sel:[1,0,0]
	v_cvt_scalef32_pk_f16_fp8 v103, v79, 1.0
	v_cvt_scalef32_pk_f16_fp8 v79, v79, 1.0 op_sel:[1,0,0]
	v_pk_fma_f16 v100, v100, v60, 0
	v_pk_fma_f16 v76, v76, v60, 0
	v_pk_fma_f16 v101, v101, v60, 0
	v_pk_fma_f16 v77, v77, v60, 0
	v_pk_fma_f16 v102, v102, v60, 0
	v_pk_fma_f16 v78, v78, v60, 0
	v_pk_fma_f16 v103, v103, v60, 0
	v_pk_fma_f16 v60, v79, v60, 0
	v_cvt_scalef32_pk_f16_fp8 v79, v72, 1.0
	v_cvt_scalef32_pk_f16_fp8 v72, v72, 1.0 op_sel:[1,0,0]
	v_pk_fma_f16 v72, v72, v61, v76
	v_cvt_scalef32_pk_f16_fp8 v76, v73, 1.0
	v_cvt_scalef32_pk_f16_fp8 v73, v73, 1.0 op_sel:[1,0,0]
	v_pk_fma_f16 v73, v73, v61, v77
	v_cvt_scalef32_pk_f16_fp8 v77, v74, 1.0
	v_cvt_scalef32_pk_f16_fp8 v74, v74, 1.0 op_sel:[1,0,0]
	v_pk_fma_f16 v74, v74, v61, v78
	v_cvt_scalef32_pk_f16_fp8 v78, v75, 1.0
	v_cvt_scalef32_pk_f16_fp8 v75, v75, 1.0 op_sel:[1,0,0]
	v_pk_fma_f16 v79, v79, v61, v100
	v_pk_fma_f16 v76, v76, v61, v101
	v_pk_fma_f16 v77, v77, v61, v102
	v_pk_fma_f16 v78, v78, v61, v103
	v_pk_fma_f16 v60, v75, v61, v60
	v_cvt_scalef32_pk_f16_fp8 v61, v68, 1.0
	v_cvt_scalef32_pk_f16_fp8 v68, v68, 1.0 op_sel:[1,0,0]
	v_pk_fma_f16 v68, v68, v62, v72
	v_cvt_scalef32_pk_f16_fp8 v72, v69, 1.0
	v_cvt_scalef32_pk_f16_fp8 v69, v69, 1.0 op_sel:[1,0,0]
	v_pk_fma_f16 v69, v69, v62, v73
	v_cvt_scalef32_pk_f16_fp8 v73, v70, 1.0
	v_cvt_scalef32_pk_f16_fp8 v70, v70, 1.0 op_sel:[1,0,0]
	v_pk_fma_f16 v70, v70, v62, v74
	v_cvt_scalef32_pk_f16_fp8 v74, v71, 1.0
	v_cvt_scalef32_pk_f16_fp8 v71, v71, 1.0 op_sel:[1,0,0]
	v_pk_fma_f16 v61, v61, v62, v79
	v_pk_fma_f16 v72, v72, v62, v76
	v_pk_fma_f16 v73, v73, v62, v77
	v_pk_fma_f16 v74, v74, v62, v78
	v_pk_fma_f16 v60, v71, v62, v60
	v_cvt_scalef32_pk_f16_fp8 v62, v64, 1.0
	v_pk_fma_f16 v61, v62, v63, v61
	v_cvt_scalef32_pk_f16_fp8 v62, v64, 1.0 op_sel:[1,0,0]
	v_cvt_scalef32_pk_f16_fp8 v64, v65, 1.0
	v_cvt_scalef32_pk_f16_fp8 v65, v65, 1.0 op_sel:[1,0,0]
	v_pk_fma_f16 v62, v62, v63, v68
	v_pk_fma_f16 v65, v65, v63, v69
	v_cvt_scalef32_pk_f16_fp8 v68, v66, 1.0
	v_cvt_scalef32_pk_f16_fp8 v66, v66, 1.0 op_sel:[1,0,0]
	v_cvt_scalef32_pk_f16_fp8 v69, v67, 1.0
	v_cvt_scalef32_pk_f16_fp8 v67, v67, 1.0 op_sel:[1,0,0]
	v_pk_fma_f16 v64, v64, v63, v72
	v_pk_fma_f16 v68, v68, v63, v73
	v_pk_fma_f16 v66, v66, v63, v70
	v_pk_fma_f16 v69, v69, v63, v74
	v_pk_fma_f16 v60, v67, v63, v60
	v_cvt_scalef32_pk_f16_fp8 v63, v56, 1.0
	v_cvt_scalef32_pk_f16_fp8 v56, v56, 1.0 op_sel:[1,0,0]
	v_pk_fma_f16 v56, v56, v36, v62
	v_cvt_scalef32_pk_f16_fp8 v62, v57, 1.0
	v_pk_fma_f16 v61, v63, v36, v61
	v_pk_fma_f16 v62, v62, v36, v64
	v_cvt_scalef32_pk_f16_fp8 v57, v57, 1.0 op_sel:[1,0,0]
	v_cvt_scalef32_pk_f16_fp8 v63, v58, 1.0
	v_cvt_scalef32_pk_f16_fp8 v58, v58, 1.0 op_sel:[1,0,0]
	v_cvt_scalef32_pk_f16_fp8 v64, v59, 1.0
	v_cvt_scalef32_pk_f16_fp8 v59, v59, 1.0 op_sel:[1,0,0]
	v_pk_fma_f16 v57, v57, v36, v65
	v_pk_fma_f16 v63, v63, v36, v68
	v_pk_fma_f16 v58, v58, v36, v66
	v_pk_fma_f16 v64, v64, v36, v69
	v_pk_fma_f16 v36, v59, v36, v60
	v_cvt_scalef32_pk_f16_fp8 v59, v52, 1.0
	v_cvt_scalef32_pk_f16_fp8 v52, v52, 1.0 op_sel:[1,0,0]
	v_pk_fma_f16 v52, v52, v37, v56
	v_cvt_scalef32_pk_f16_fp8 v56, v53, 1.0
	v_cvt_scalef32_pk_f16_fp8 v53, v53, 1.0 op_sel:[1,0,0]
	v_pk_fma_f16 v53, v53, v37, v57
	v_cvt_scalef32_pk_f16_fp8 v57, v54, 1.0
	v_cvt_scalef32_pk_f16_fp8 v54, v54, 1.0 op_sel:[1,0,0]
	v_pk_fma_f16 v54, v54, v37, v58
	v_cvt_scalef32_pk_f16_fp8 v58, v55, 1.0
	v_cvt_scalef32_pk_f16_fp8 v55, v55, 1.0 op_sel:[1,0,0]
	v_pk_fma_f16 v59, v59, v37, v61
	v_pk_fma_f16 v56, v56, v37, v62
	v_pk_fma_f16 v57, v57, v37, v63
	v_pk_fma_f16 v58, v58, v37, v64
	v_pk_fma_f16 v36, v55, v37, v36
	v_cvt_scalef32_pk_f16_fp8 v37, v48, 1.0
	v_cvt_scalef32_pk_f16_fp8 v48, v48, 1.0 op_sel:[1,0,0]
	v_pk_fma_f16 v48, v48, v38, v52
	v_cvt_scalef32_pk_f16_fp8 v52, v49, 1.0
	v_cvt_scalef32_pk_f16_fp8 v49, v49, 1.0 op_sel:[1,0,0]
	v_pk_fma_f16 v49, v49, v38, v53
	v_cvt_scalef32_pk_f16_fp8 v53, v50, 1.0
	v_cvt_scalef32_pk_f16_fp8 v50, v50, 1.0 op_sel:[1,0,0]
	v_pk_fma_f16 v50, v50, v38, v54
	v_cvt_scalef32_pk_f16_fp8 v54, v51, 1.0
	v_cvt_scalef32_pk_f16_fp8 v51, v51, 1.0 op_sel:[1,0,0]
	v_pk_fma_f16 v37, v37, v38, v59
	v_pk_fma_f16 v52, v52, v38, v56
	v_pk_fma_f16 v53, v53, v38, v57
	v_pk_fma_f16 v54, v54, v38, v58
	v_pk_fma_f16 v36, v51, v38, v36
	v_cvt_scalef32_pk_f16_fp8 v38, v44, 1.0
	v_pk_fma_f16 v37, v38, v39, v37
	v_cvt_scalef32_pk_f16_fp8 v38, v44, 1.0 op_sel:[1,0,0]
	v_cvt_scalef32_pk_f16_fp8 v44, v45, 1.0
	v_cvt_scalef32_pk_f16_fp8 v45, v45, 1.0 op_sel:[1,0,0]
	v_pk_fma_f16 v38, v38, v39, v48
	v_pk_fma_f16 v45, v45, v39, v49
	v_cvt_scalef32_pk_f16_fp8 v48, v46, 1.0
	v_cvt_scalef32_pk_f16_fp8 v46, v46, 1.0 op_sel:[1,0,0]
	v_cvt_scalef32_pk_f16_fp8 v49, v47, 1.0
	v_cvt_scalef32_pk_f16_fp8 v47, v47, 1.0 op_sel:[1,0,0]
	v_pk_fma_f16 v44, v44, v39, v52
	v_pk_fma_f16 v48, v48, v39, v53
	v_pk_fma_f16 v46, v46, v39, v50
	v_pk_fma_f16 v49, v49, v39, v54
	v_pk_fma_f16 v36, v47, v39, v36
	v_cvt_scalef32_pk_f16_fp8 v39, v40, 1.0
	v_pk_fma_f16 v37, v39, v12, v37
	v_cvt_scalef32_pk_f16_fp8 v39, v40, 1.0 op_sel:[1,0,0]
	v_pk_fma_f16 v38, v39, v12, v38
	v_cvt_scalef32_pk_f16_fp8 v39, v41, 1.0
	v_pk_fma_f16 v39, v39, v12, v44
	v_cvt_scalef32_pk_f16_fp8 v40, v41, 1.0 op_sel:[1,0,0]
	v_cvt_scalef32_pk_f16_fp8 v41, v42, 1.0
	v_cvt_scalef32_pk_f16_fp8 v42, v42, 1.0 op_sel:[1,0,0]
	v_cvt_scalef32_pk_f16_fp8 v44, v43, 1.0
	v_cvt_scalef32_pk_f16_fp8 v43, v43, 1.0 op_sel:[1,0,0]
	v_pk_fma_f16 v40, v40, v12, v45
	v_pk_fma_f16 v41, v41, v12, v48
	v_pk_fma_f16 v42, v42, v12, v46
	v_pk_fma_f16 v44, v44, v12, v49
	v_pk_fma_f16 v12, v43, v12, v36
	v_cvt_scalef32_pk_f16_fp8 v36, v32, 1.0
	v_pk_fma_f16 v36, v36, v13, v37
	v_cvt_scalef32_pk_f16_fp8 v32, v32, 1.0 op_sel:[1,0,0]
	v_cvt_scalef32_pk_f16_fp8 v37, v33, 1.0
	v_pk_fma_f16 v32, v32, v13, v38
	v_pk_fma_f16 v37, v37, v13, v39
	v_cvt_scalef32_pk_f16_fp8 v33, v33, 1.0 op_sel:[1,0,0]
	v_cvt_scalef32_pk_f16_fp8 v38, v34, 1.0
	v_cvt_scalef32_pk_f16_fp8 v34, v34, 1.0 op_sel:[1,0,0]
	v_cvt_scalef32_pk_f16_fp8 v39, v35, 1.0
	v_cvt_scalef32_pk_f16_fp8 v35, v35, 1.0 op_sel:[1,0,0]
	v_pk_fma_f16 v33, v33, v13, v40
	v_pk_fma_f16 v38, v38, v13, v41
	v_pk_fma_f16 v34, v34, v13, v42
	v_pk_fma_f16 v39, v39, v13, v44
	v_pk_fma_f16 v12, v35, v13, v12
	v_cvt_scalef32_pk_f16_fp8 v13, v28, 1.0
	v_cvt_scalef32_pk_f16_fp8 v28, v28, 1.0 op_sel:[1,0,0]
	v_pk_fma_f16 v28, v28, v14, v32
	v_cvt_scalef32_pk_f16_fp8 v32, v29, 1.0
	v_cvt_scalef32_pk_f16_fp8 v29, v29, 1.0 op_sel:[1,0,0]
	v_pk_fma_f16 v29, v29, v14, v33
	v_cvt_scalef32_pk_f16_fp8 v33, v30, 1.0
	v_cvt_scalef32_pk_f16_fp8 v30, v30, 1.0 op_sel:[1,0,0]
	v_pk_fma_f16 v30, v30, v14, v34
	v_cvt_scalef32_pk_f16_fp8 v34, v31, 1.0
	v_cvt_scalef32_pk_f16_fp8 v31, v31, 1.0 op_sel:[1,0,0]
	v_pk_fma_f16 v13, v13, v14, v36
	v_pk_fma_f16 v32, v32, v14, v37
	v_pk_fma_f16 v33, v33, v14, v38
	v_pk_fma_f16 v34, v34, v14, v39
	v_pk_fma_f16 v12, v31, v14, v12
	v_cvt_scalef32_pk_f16_fp8 v14, v24, 1.0
	v_pk_fma_f16 v13, v14, v15, v13
	v_cvt_scalef32_pk_f16_fp8 v14, v24, 1.0 op_sel:[1,0,0]
	v_cvt_scalef32_pk_f16_fp8 v24, v25, 1.0
	v_cvt_scalef32_pk_f16_fp8 v25, v25, 1.0 op_sel:[1,0,0]
	v_pk_fma_f16 v14, v14, v15, v28
	v_pk_fma_f16 v25, v25, v15, v29
	v_cvt_scalef32_pk_f16_fp8 v28, v26, 1.0
	v_cvt_scalef32_pk_f16_fp8 v26, v26, 1.0 op_sel:[1,0,0]
	v_cvt_scalef32_pk_f16_fp8 v29, v27, 1.0
	v_cvt_scalef32_pk_f16_fp8 v27, v27, 1.0 op_sel:[1,0,0]
	v_pk_fma_f16 v24, v24, v15, v32
	v_pk_fma_f16 v28, v28, v15, v33
	v_pk_fma_f16 v26, v26, v15, v30
	v_pk_fma_f16 v29, v29, v15, v34
	v_pk_fma_f16 v12, v27, v15, v12
	v_cvt_scalef32_pk_f16_fp8 v15, v20, 1.0
	v_pk_fma_f16 v13, v15, v0, v13
	v_cvt_scalef32_pk_f16_fp8 v15, v20, 1.0 op_sel:[1,0,0]
	v_pk_fma_f16 v14, v15, v0, v14
	v_cvt_scalef32_pk_f16_fp8 v15, v21, 1.0
	v_pk_fma_f16 v15, v15, v0, v24
	v_cvt_scalef32_pk_f16_fp8 v20, v21, 1.0 op_sel:[1,0,0]
	v_cvt_scalef32_pk_f16_fp8 v21, v22, 1.0
	v_cvt_scalef32_pk_f16_fp8 v22, v22, 1.0 op_sel:[1,0,0]
	v_cvt_scalef32_pk_f16_fp8 v24, v23, 1.0
	v_cvt_scalef32_pk_f16_fp8 v23, v23, 1.0 op_sel:[1,0,0]
	v_pk_fma_f16 v20, v20, v0, v25
	v_pk_fma_f16 v21, v21, v0, v28
	v_pk_fma_f16 v22, v22, v0, v26
	v_pk_fma_f16 v24, v24, v0, v29
	v_pk_fma_f16 v0, v23, v0, v12
	v_cvt_scalef32_pk_f16_fp8 v12, v16, 1.0
	v_pk_fma_f16 v12, v12, v1, v13
	v_cvt_scalef32_pk_f16_fp8 v13, v16, 1.0 op_sel:[1,0,0]
	v_pk_fma_f16 v13, v13, v1, v14
	v_cvt_scalef32_pk_f16_fp8 v14, v17, 1.0
	v_pk_fma_f16 v14, v14, v1, v15
	v_cvt_scalef32_pk_f16_fp8 v15, v17, 1.0 op_sel:[1,0,0]
	v_cvt_scalef32_pk_f16_fp8 v16, v18, 1.0
	v_cvt_scalef32_pk_f16_fp8 v17, v18, 1.0 op_sel:[1,0,0]
	v_cvt_scalef32_pk_f16_fp8 v18, v19, 1.0
	v_cvt_scalef32_pk_f16_fp8 v19, v19, 1.0 op_sel:[1,0,0]
	v_pk_fma_f16 v15, v15, v1, v20
	v_pk_fma_f16 v16, v16, v1, v21
	v_pk_fma_f16 v17, v17, v1, v22
	v_pk_fma_f16 v18, v18, v1, v24
	v_pk_fma_f16 v0, v19, v1, v0
	v_cvt_scalef32_pk_f16_fp8 v1, v4, 1.0
	v_pk_fma_f16 v1, v1, v2, v12
	v_cvt_scalef32_pk_f16_fp8 v4, v4, 1.0 op_sel:[1,0,0]
	v_cvt_scalef32_pk_f16_fp8 v12, v5, 1.0
	v_pk_fma_f16 v4, v4, v2, v13
	v_pk_fma_f16 v12, v12, v2, v14
	v_cvt_scalef32_pk_f16_fp8 v5, v5, 1.0 op_sel:[1,0,0]
	v_cvt_scalef32_pk_f16_fp8 v13, v6, 1.0
	v_cvt_scalef32_pk_f16_fp8 v6, v6, 1.0 op_sel:[1,0,0]
	v_cvt_scalef32_pk_f16_fp8 v14, v7, 1.0
	v_cvt_scalef32_pk_f16_fp8 v7, v7, 1.0 op_sel:[1,0,0]
	v_pk_fma_f16 v5, v5, v2, v15
	v_pk_fma_f16 v13, v13, v2, v16
	v_pk_fma_f16 v6, v6, v2, v17
	v_pk_fma_f16 v14, v14, v2, v18
	v_pk_fma_f16 v0, v7, v2, v0
	v_cvt_scalef32_pk_f16_fp8 v2, v8, 1.0
	v_pk_fma_f16 v1, v2, v3, v1
	v_cvt_scalef32_pk_f16_fp8 v2, v8, 1.0 op_sel:[1,0,0]
	v_cvt_scalef32_pk_f16_fp8 v7, v9, 1.0 op_sel:[1,0,0]
	v_cvt_scalef32_pk_f16_fp8 v8, v10, 1.0 op_sel:[1,0,0]
	v_pk_fma_f16 v2, v2, v3, v4
	v_cvt_scalef32_pk_f16_fp8 v4, v9, 1.0
	v_pk_fma_f16 v5, v7, v3, v5
	v_cvt_scalef32_pk_f16_fp8 v7, v10, 1.0
	v_pk_fma_f16 v6, v8, v3, v6
	v_cvt_scalef32_pk_f16_fp8 v8, v11, 1.0
	v_cvt_scalef32_pk_f16_fp8 v9, v11, 1.0 op_sel:[1,0,0]
	v_pk_fma_f16 v4, v4, v3, v12
	v_pk_fma_f16 v7, v7, v3, v13
	v_pk_fma_f16 v8, v8, v3, v14
	v_pk_fma_f16 v0, v9, v3, v0
	v_permlane32_swap_b32_e32 v1, v7
	v_permlane32_swap_b32_e32 v2, v6
	v_permlane32_swap_b32_e32 v4, v8
	v_permlane32_swap_b32_e32 v5, v0
	v_pk_add_f16 v1, v1, v7
	v_pk_add_f16 v2, v2, v6
	v_pk_add_f16 v3, v4, v8
	v_pk_add_f16 v0, v5, v0
	s_nop 0
	v_permlane16_swap_b32_e32 v1, v3
	v_permlane16_swap_b32_e32 v2, v0
	v_pk_add_f16 v1, v1, v3
	v_pk_add_f16 v0, v2, v0
	s_ashr_i32 s17, s16, 31
	v_cndmask_b32_e64 v2, v1, v0, s[2:3]
	v_cndmask_b32_e64 v0, v0, v1, s[2:3]
	s_lshl_b64 s[16:17], s[16:17], 11
	v_mov_b32_dpp v1, v2 row_ror:8 row_mask:0xf bank_mask:0xf bound_ctrl:1
	v_pk_add_f16 v1, v1, v0
	s_add_u32 s24, s14, s16
	v_cvt_f32_f16_e32 v0, v1
	v_cvt_f32_f16_sdwa v1, v1 dst_sel:DWORD dst_unused:UNUSED_PAD src0_sel:WORD_1
	s_addc_u32 s25, s15, s17
	s_lshl_b32 s16, s9, 7
	s_ashr_i32 s17, s16, 31
	v_pk_mul_f32 v[0:1], v[0:1], s[10:11] op_sel_hi:[1,0]
	s_lshl_b64 s[16:17], s[16:17], 1
	v_and_b32_sdwa v3, v0, v208 dst_sel:DWORD dst_unused:UNUSED_PAD src0_sel:WORD_1 src1_sel:DWORD
	v_and_b32_sdwa v2, v1, v208 dst_sel:DWORD dst_unused:UNUSED_PAD src0_sel:WORD_1 src1_sel:DWORD
	v_add3_u32 v0, v0, v3, s7
	s_add_u32 s16, s24, s16
	v_add3_u32 v1, v1, v2, s7
	v_lshrrev_b32_e32 v0, 16, v0
	s_addc_u32 s17, s25, s17
	v_and_or_b32 v2, v1, s11, v0
	v_lshl_add_u64 v[0:1], s[16:17], 0, v[194:195]
	s_mov_b32 s18, s27
	s_mov_b32 s23, s26
	v_lshl_add_u64 v[0:1], v[0:1], 0, v[204:205]
	s_cmp_gt_i32 s22, 7
	s_mov_b64 s[16:17], -1
	global_store_dword v[0:1], v2, off
	s_cbranch_scc1 .LBB0_621
	s_add_i32 s9, s23, s19
	s_cmpk_gt_i32 s9, 0x3fff
	s_cselect_b32 s25, s33, 0
	s_cselect_b32 s24, s6, s9
	s_add_i32 s25, s25, s18
	s_and_b64 s[16:17], s[20:21], exec
	s_cselect_b32 s9, s18, s22
	v_lshl_or_b32 v0, s9, 21, v196
	s_waitcnt vmcnt(1)
	ds_swizzle_b32 v188, v250 offset:24
	ds_swizzle_b32 v189, v251 offset:24
	ds_swizzle_b32 v190, v250 offset:56
	ds_swizzle_b32 v191, v251 offset:56
	ds_swizzle_b32 v184, v250 offset:88
	ds_swizzle_b32 v185, v251 offset:88
	ds_swizzle_b32 v186, v250 offset:120
	ds_swizzle_b32 v187, v251 offset:120
	ds_swizzle_b32 v180, v250 offset:152
	ds_swizzle_b32 v181, v251 offset:152
	ds_swizzle_b32 v182, v250 offset:184
	ds_swizzle_b32 v183, v251 offset:184
	ds_swizzle_b32 v176, v250 offset:216
	ds_swizzle_b32 v177, v251 offset:216
	ds_swizzle_b32 v178, v250 offset:248
	ds_swizzle_b32 v179, v251 offset:248
	ds_swizzle_b32 v172, v248 offset:24
	ds_swizzle_b32 v173, v249 offset:24
	ds_swizzle_b32 v174, v248 offset:56
	ds_swizzle_b32 v175, v249 offset:56
	ds_swizzle_b32 v148, v248 offset:88
	ds_swizzle_b32 v149, v249 offset:88
	ds_swizzle_b32 v150, v248 offset:120
	ds_swizzle_b32 v151, v249 offset:120
	ds_swizzle_b32 v116, v248 offset:152
	ds_swizzle_b32 v117, v249 offset:152
	ds_swizzle_b32 v118, v248 offset:184
	ds_swizzle_b32 v119, v249 offset:184
	ds_swizzle_b32 v84, v248 offset:216
	ds_swizzle_b32 v85, v249 offset:216
	ds_swizzle_b32 v86, v248 offset:248
	ds_swizzle_b32 v87, v249 offset:248
	s_waitcnt lgkmcnt(0)
	s_nop 0
	v_lshl_add_u32 v1, v188, 7, v0
	s_cselect_b32 s16, s23, s8
	v_lshl_add_u32 v2, v189, 7, v0
	global_load_dwordx4 v[76:79], v1, s[4:5]
	global_load_dwordx4 v[72:75], v2, s[4:5]
	v_lshl_add_u32 v1, v190, 7, v0
	s_ashr_i32 s17, s16, 31
	v_lshl_add_u32 v2, v191, 7, v0
	global_load_dwordx4 v[68:71], v1, s[4:5]
	global_load_dwordx4 v[64:67], v2, s[4:5]
	v_lshl_add_u32 v1, v184, 7, v0
	s_lshl_b64 s[16:17], s[16:17], 9
	v_lshl_add_u32 v2, v185, 7, v0
	global_load_dwordx4 v[56:59], v1, s[4:5]
	global_load_dwordx4 v[52:55], v2, s[4:5]
	v_lshl_add_u32 v1, v186, 7, v0
	s_cmp_lt_i32 s25, 8
	v_lshl_add_u32 v2, v187, 7, v0
	global_load_dwordx4 v[48:51], v1, s[4:5]
	global_load_dwordx4 v[44:47], v2, s[4:5]
	v_lshl_add_u32 v1, v180, 7, v0
	v_lshl_add_u64 v[60:61], v[244:245], 0, s[16:17]
	s_cselect_b32 s16, s24, s8
	v_lshl_add_u32 v2, v181, 7, v0
	global_load_dwordx4 v[40:43], v1, s[4:5]
	global_load_dwordx4 v[32:35], v2, s[4:5]
	v_lshl_add_u32 v1, v182, 7, v0
	s_ashr_i32 s17, s16, 31
	v_lshl_add_u32 v2, v183, 7, v0
	global_load_dwordx4 v[28:31], v1, s[4:5]
	global_load_dwordx4 v[24:27], v2, s[4:5]
	v_lshl_add_u32 v1, v176, 7, v0
	s_lshl_b64 s[16:17], s[16:17], 9
	v_lshl_add_u32 v2, v177, 7, v0
	global_load_dwordx4 v[20:23], v1, s[4:5]
	global_load_dwordx4 v[16:19], v2, s[4:5]
	v_lshl_add_u32 v1, v178, 7, v0
	v_lshl_add_u32 v0, v179, 7, v0
	v_lshl_add_u64 v[140:141], v[246:247], 0, s[16:17]
	global_load_dwordx4 v[4:7], v1, s[4:5]
	global_load_dwordx4 v[8:11], v0, s[4:5]
	s_nop 0
	global_load_dwordx2 v[248:249], v[60:61], off
	s_nop 0
	global_load_dwordx2 v[250:251], v[140:141], off
	v_cvt_scalef32_pk_f16_fp8 v176, v168, 1.0
	v_cvt_scalef32_pk_f16_fp8 v168, v168, 1.0 op_sel:[1,0,0]
	v_cvt_scalef32_pk_f16_fp8 v177, v169, 1.0
	v_cvt_scalef32_pk_f16_fp8 v169, v169, 1.0 op_sel:[1,0,0]
	v_cvt_scalef32_pk_f16_fp8 v178, v170, 1.0
	v_cvt_scalef32_pk_f16_fp8 v170, v170, 1.0 op_sel:[1,0,0]
	v_cvt_scalef32_pk_f16_fp8 v179, v171, 1.0
	v_cvt_scalef32_pk_f16_fp8 v171, v171, 1.0 op_sel:[1,0,0]
	v_pk_fma_f16 v176, v176, v172, 0
	v_pk_fma_f16 v168, v168, v172, 0
	v_pk_fma_f16 v177, v177, v172, 0
	v_pk_fma_f16 v169, v169, v172, 0
	v_pk_fma_f16 v178, v178, v172, 0
	v_pk_fma_f16 v170, v170, v172, 0
	v_pk_fma_f16 v179, v179, v172, 0
	v_pk_fma_f16 v171, v171, v172, 0
	v_cvt_scalef32_pk_f16_fp8 v172, v164, 1.0
	v_cvt_scalef32_pk_f16_fp8 v164, v164, 1.0 op_sel:[1,0,0]
	v_pk_fma_f16 v164, v164, v173, v168
	v_cvt_scalef32_pk_f16_fp8 v168, v165, 1.0
	v_cvt_scalef32_pk_f16_fp8 v165, v165, 1.0 op_sel:[1,0,0]
	v_pk_fma_f16 v165, v165, v173, v169
	v_cvt_scalef32_pk_f16_fp8 v169, v166, 1.0
	v_cvt_scalef32_pk_f16_fp8 v166, v166, 1.0 op_sel:[1,0,0]
	v_pk_fma_f16 v166, v166, v173, v170
	v_cvt_scalef32_pk_f16_fp8 v170, v167, 1.0
	v_cvt_scalef32_pk_f16_fp8 v167, v167, 1.0 op_sel:[1,0,0]
	v_pk_fma_f16 v167, v167, v173, v171
	v_cvt_scalef32_pk_f16_fp8 v171, v160, 1.0
	v_cvt_scalef32_pk_f16_fp8 v160, v160, 1.0 op_sel:[1,0,0]
	v_pk_fma_f16 v160, v160, v174, v164
	v_cvt_scalef32_pk_f16_fp8 v164, v161, 1.0
	v_cvt_scalef32_pk_f16_fp8 v161, v161, 1.0 op_sel:[1,0,0]
	v_pk_fma_f16 v161, v161, v174, v165
	v_cvt_scalef32_pk_f16_fp8 v165, v162, 1.0
	v_cvt_scalef32_pk_f16_fp8 v162, v162, 1.0 op_sel:[1,0,0]
	v_pk_fma_f16 v162, v162, v174, v166
	v_cvt_scalef32_pk_f16_fp8 v166, v163, 1.0
	v_cvt_scalef32_pk_f16_fp8 v163, v163, 1.0 op_sel:[1,0,0]
	v_pk_fma_f16 v163, v163, v174, v167
	v_cvt_scalef32_pk_f16_fp8 v167, v156, 1.0
	v_cvt_scalef32_pk_f16_fp8 v156, v156, 1.0 op_sel:[1,0,0]
	v_pk_fma_f16 v156, v156, v175, v160
	v_cvt_scalef32_pk_f16_fp8 v160, v157, 1.0
	v_cvt_scalef32_pk_f16_fp8 v157, v157, 1.0 op_sel:[1,0,0]
	v_pk_fma_f16 v157, v157, v175, v161
	v_cvt_scalef32_pk_f16_fp8 v161, v158, 1.0
	v_cvt_scalef32_pk_f16_fp8 v158, v158, 1.0 op_sel:[1,0,0]
	v_pk_fma_f16 v158, v158, v175, v162
	v_cvt_scalef32_pk_f16_fp8 v162, v159, 1.0
	v_cvt_scalef32_pk_f16_fp8 v159, v159, 1.0 op_sel:[1,0,0]
	v_pk_fma_f16 v159, v159, v175, v163
	v_cvt_scalef32_pk_f16_fp8 v163, v152, 1.0
	v_cvt_scalef32_pk_f16_fp8 v152, v152, 1.0 op_sel:[1,0,0]
	v_pk_fma_f16 v172, v172, v173, v176
	v_pk_fma_f16 v168, v168, v173, v177
	v_pk_fma_f16 v169, v169, v173, v178
	v_pk_fma_f16 v170, v170, v173, v179
	v_pk_fma_f16 v152, v152, v148, v156
	v_cvt_scalef32_pk_f16_fp8 v156, v153, 1.0
	v_cvt_scalef32_pk_f16_fp8 v153, v153, 1.0 op_sel:[1,0,0]
	v_pk_fma_f16 v171, v171, v174, v172
	v_pk_fma_f16 v164, v164, v174, v168
	v_pk_fma_f16 v165, v165, v174, v169
	v_pk_fma_f16 v166, v166, v174, v170
	v_pk_fma_f16 v153, v153, v148, v157
	v_cvt_scalef32_pk_f16_fp8 v157, v154, 1.0
	v_cvt_scalef32_pk_f16_fp8 v154, v154, 1.0 op_sel:[1,0,0]
	v_pk_fma_f16 v167, v167, v175, v171
	v_pk_fma_f16 v160, v160, v175, v164
	v_pk_fma_f16 v161, v161, v175, v165
	v_pk_fma_f16 v162, v162, v175, v166
	v_pk_fma_f16 v154, v154, v148, v158
	v_cvt_scalef32_pk_f16_fp8 v158, v155, 1.0
	v_cvt_scalef32_pk_f16_fp8 v155, v155, 1.0 op_sel:[1,0,0]
	v_pk_fma_f16 v163, v163, v148, v167
	v_pk_fma_f16 v156, v156, v148, v160
	v_pk_fma_f16 v157, v157, v148, v161
	v_pk_fma_f16 v158, v158, v148, v162
	v_pk_fma_f16 v148, v155, v148, v159
	v_cvt_scalef32_pk_f16_fp8 v155, v144, 1.0
	v_cvt_scalef32_pk_f16_fp8 v144, v144, 1.0 op_sel:[1,0,0]
	v_pk_fma_f16 v144, v144, v149, v152
	v_cvt_scalef32_pk_f16_fp8 v152, v145, 1.0
	v_cvt_scalef32_pk_f16_fp8 v145, v145, 1.0 op_sel:[1,0,0]
	v_pk_fma_f16 v145, v145, v149, v153
	v_cvt_scalef32_pk_f16_fp8 v153, v146, 1.0
	v_cvt_scalef32_pk_f16_fp8 v146, v146, 1.0 op_sel:[1,0,0]
	v_pk_fma_f16 v146, v146, v149, v154
	v_cvt_scalef32_pk_f16_fp8 v154, v147, 1.0
	v_cvt_scalef32_pk_f16_fp8 v147, v147, 1.0 op_sel:[1,0,0]
	v_pk_fma_f16 v147, v147, v149, v148
	v_cvt_scalef32_pk_f16_fp8 v148, v136, 1.0
	v_cvt_scalef32_pk_f16_fp8 v136, v136, 1.0 op_sel:[1,0,0]
	v_pk_fma_f16 v136, v136, v150, v144
	v_cvt_scalef32_pk_f16_fp8 v144, v137, 1.0
	v_cvt_scalef32_pk_f16_fp8 v137, v137, 1.0 op_sel:[1,0,0]
	v_pk_fma_f16 v137, v137, v150, v145
	v_cvt_scalef32_pk_f16_fp8 v145, v138, 1.0
	v_cvt_scalef32_pk_f16_fp8 v138, v138, 1.0 op_sel:[1,0,0]
	v_pk_fma_f16 v138, v138, v150, v146
	v_cvt_scalef32_pk_f16_fp8 v146, v139, 1.0
	v_cvt_scalef32_pk_f16_fp8 v139, v139, 1.0 op_sel:[1,0,0]
	v_pk_fma_f16 v139, v139, v150, v147
	v_cvt_scalef32_pk_f16_fp8 v147, v128, 1.0
	v_cvt_scalef32_pk_f16_fp8 v128, v128, 1.0 op_sel:[1,0,0]
	v_pk_fma_f16 v128, v128, v151, v136
	v_cvt_scalef32_pk_f16_fp8 v136, v129, 1.0
	v_cvt_scalef32_pk_f16_fp8 v129, v129, 1.0 op_sel:[1,0,0]
	v_pk_fma_f16 v129, v129, v151, v137
	v_cvt_scalef32_pk_f16_fp8 v137, v130, 1.0
	v_cvt_scalef32_pk_f16_fp8 v130, v130, 1.0 op_sel:[1,0,0]
	v_pk_fma_f16 v130, v130, v151, v138
	v_cvt_scalef32_pk_f16_fp8 v138, v131, 1.0
	v_cvt_scalef32_pk_f16_fp8 v131, v131, 1.0 op_sel:[1,0,0]
	v_pk_fma_f16 v131, v131, v151, v139
	v_cvt_scalef32_pk_f16_fp8 v139, v124, 1.0
	v_cvt_scalef32_pk_f16_fp8 v124, v124, 1.0 op_sel:[1,0,0]
	v_pk_fma_f16 v155, v155, v149, v163
	v_pk_fma_f16 v152, v152, v149, v156
	v_pk_fma_f16 v153, v153, v149, v157
	v_pk_fma_f16 v154, v154, v149, v158
	v_pk_fma_f16 v124, v124, v116, v128
	v_cvt_scalef32_pk_f16_fp8 v128, v125, 1.0
	v_cvt_scalef32_pk_f16_fp8 v125, v125, 1.0 op_sel:[1,0,0]
	v_pk_fma_f16 v148, v148, v150, v155
	v_pk_fma_f16 v144, v144, v150, v152
	v_pk_fma_f16 v145, v145, v150, v153
	v_pk_fma_f16 v146, v146, v150, v154
	v_pk_fma_f16 v125, v125, v116, v129
	v_cvt_scalef32_pk_f16_fp8 v129, v126, 1.0
	v_cvt_scalef32_pk_f16_fp8 v126, v126, 1.0 op_sel:[1,0,0]
	v_pk_fma_f16 v147, v147, v151, v148
	v_pk_fma_f16 v136, v136, v151, v144
	v_pk_fma_f16 v137, v137, v151, v145
	v_pk_fma_f16 v138, v138, v151, v146
	v_pk_fma_f16 v126, v126, v116, v130
	v_cvt_scalef32_pk_f16_fp8 v130, v127, 1.0
	v_cvt_scalef32_pk_f16_fp8 v127, v127, 1.0 op_sel:[1,0,0]
	v_pk_fma_f16 v139, v139, v116, v147
	v_pk_fma_f16 v128, v128, v116, v136
	v_pk_fma_f16 v129, v129, v116, v137
	v_pk_fma_f16 v130, v130, v116, v138
	v_pk_fma_f16 v116, v127, v116, v131
	v_cvt_scalef32_pk_f16_fp8 v127, v120, 1.0
	v_cvt_scalef32_pk_f16_fp8 v120, v120, 1.0 op_sel:[1,0,0]
	v_pk_fma_f16 v120, v120, v117, v124
	v_cvt_scalef32_pk_f16_fp8 v124, v121, 1.0
	v_cvt_scalef32_pk_f16_fp8 v121, v121, 1.0 op_sel:[1,0,0]
	v_pk_fma_f16 v121, v121, v117, v125
	v_cvt_scalef32_pk_f16_fp8 v125, v122, 1.0
	v_cvt_scalef32_pk_f16_fp8 v122, v122, 1.0 op_sel:[1,0,0]
	v_pk_fma_f16 v122, v122, v117, v126
	v_cvt_scalef32_pk_f16_fp8 v126, v123, 1.0
	v_cvt_scalef32_pk_f16_fp8 v123, v123, 1.0 op_sel:[1,0,0]
	v_pk_fma_f16 v127, v127, v117, v139
	v_pk_fma_f16 v124, v124, v117, v128
	v_pk_fma_f16 v125, v125, v117, v129
	v_pk_fma_f16 v126, v126, v117, v130
	v_pk_fma_f16 v116, v123, v117, v116
	v_cvt_scalef32_pk_f16_fp8 v117, v112, 1.0
	v_cvt_scalef32_pk_f16_fp8 v112, v112, 1.0 op_sel:[1,0,0]
	v_pk_fma_f16 v112, v112, v118, v120
	v_cvt_scalef32_pk_f16_fp8 v120, v113, 1.0
	v_cvt_scalef32_pk_f16_fp8 v113, v113, 1.0 op_sel:[1,0,0]
	v_pk_fma_f16 v113, v113, v118, v121
	v_cvt_scalef32_pk_f16_fp8 v121, v114, 1.0
	v_cvt_scalef32_pk_f16_fp8 v114, v114, 1.0 op_sel:[1,0,0]
	v_pk_fma_f16 v114, v114, v118, v122
	v_cvt_scalef32_pk_f16_fp8 v122, v115, 1.0
	v_cvt_scalef32_pk_f16_fp8 v115, v115, 1.0 op_sel:[1,0,0]
	v_pk_fma_f16 v115, v115, v118, v116
	v_cvt_scalef32_pk_f16_fp8 v116, v104, 1.0
	v_cvt_scalef32_pk_f16_fp8 v104, v104, 1.0 op_sel:[1,0,0]
	v_pk_fma_f16 v104, v104, v119, v112
	v_cvt_scalef32_pk_f16_fp8 v112, v105, 1.0
	v_cvt_scalef32_pk_f16_fp8 v105, v105, 1.0 op_sel:[1,0,0]
	v_pk_fma_f16 v105, v105, v119, v113
	v_cvt_scalef32_pk_f16_fp8 v113, v106, 1.0
	v_cvt_scalef32_pk_f16_fp8 v106, v106, 1.0 op_sel:[1,0,0]
	v_pk_fma_f16 v106, v106, v119, v114
	v_cvt_scalef32_pk_f16_fp8 v114, v107, 1.0
	v_cvt_scalef32_pk_f16_fp8 v107, v107, 1.0 op_sel:[1,0,0]
	v_pk_fma_f16 v107, v107, v119, v115
	v_cvt_scalef32_pk_f16_fp8 v115, v96, 1.0
	v_cvt_scalef32_pk_f16_fp8 v96, v96, 1.0 op_sel:[1,0,0]
	v_pk_fma_f16 v96, v96, v84, v104
	v_cvt_scalef32_pk_f16_fp8 v104, v97, 1.0
	v_cvt_scalef32_pk_f16_fp8 v97, v97, 1.0 op_sel:[1,0,0]
	v_pk_fma_f16 v117, v117, v118, v127
	v_pk_fma_f16 v120, v120, v118, v124
	v_pk_fma_f16 v121, v121, v118, v125
	v_pk_fma_f16 v122, v122, v118, v126
	v_pk_fma_f16 v97, v97, v84, v105
	v_cvt_scalef32_pk_f16_fp8 v105, v98, 1.0
	v_cvt_scalef32_pk_f16_fp8 v98, v98, 1.0 op_sel:[1,0,0]
	v_pk_fma_f16 v116, v116, v119, v117
	v_pk_fma_f16 v112, v112, v119, v120
	v_pk_fma_f16 v113, v113, v119, v121
	v_pk_fma_f16 v114, v114, v119, v122
	v_pk_fma_f16 v98, v98, v84, v106
	v_cvt_scalef32_pk_f16_fp8 v106, v99, 1.0
	v_cvt_scalef32_pk_f16_fp8 v99, v99, 1.0 op_sel:[1,0,0]
	v_pk_fma_f16 v115, v115, v84, v116
	v_pk_fma_f16 v104, v104, v84, v112
	v_pk_fma_f16 v105, v105, v84, v113
	v_pk_fma_f16 v106, v106, v84, v114
	v_pk_fma_f16 v84, v99, v84, v107
	v_cvt_scalef32_pk_f16_fp8 v99, v92, 1.0
	v_cvt_scalef32_pk_f16_fp8 v92, v92, 1.0 op_sel:[1,0,0]
	v_pk_fma_f16 v92, v92, v85, v96
	v_cvt_scalef32_pk_f16_fp8 v96, v93, 1.0
	v_cvt_scalef32_pk_f16_fp8 v93, v93, 1.0 op_sel:[1,0,0]
	v_pk_fma_f16 v93, v93, v85, v97
	v_cvt_scalef32_pk_f16_fp8 v97, v94, 1.0
	v_cvt_scalef32_pk_f16_fp8 v94, v94, 1.0 op_sel:[1,0,0]
	v_pk_fma_f16 v94, v94, v85, v98
	v_cvt_scalef32_pk_f16_fp8 v98, v95, 1.0
	v_cvt_scalef32_pk_f16_fp8 v95, v95, 1.0 op_sel:[1,0,0]
	v_pk_fma_f16 v99, v99, v85, v115
	v_pk_fma_f16 v96, v96, v85, v104
	v_pk_fma_f16 v97, v97, v85, v105
	v_pk_fma_f16 v98, v98, v85, v106
	v_pk_fma_f16 v84, v95, v85, v84
	v_cvt_scalef32_pk_f16_fp8 v85, v88, 1.0
	v_cvt_scalef32_pk_f16_fp8 v88, v88, 1.0 op_sel:[1,0,0]
	v_pk_fma_f16 v88, v88, v86, v92
	v_cvt_scalef32_pk_f16_fp8 v92, v89, 1.0
	v_cvt_scalef32_pk_f16_fp8 v89, v89, 1.0 op_sel:[1,0,0]
	v_pk_fma_f16 v89, v89, v86, v93
	v_cvt_scalef32_pk_f16_fp8 v93, v90, 1.0
	v_cvt_scalef32_pk_f16_fp8 v90, v90, 1.0 op_sel:[1,0,0]
	v_pk_fma_f16 v90, v90, v86, v94
	v_cvt_scalef32_pk_f16_fp8 v94, v91, 1.0
	v_cvt_scalef32_pk_f16_fp8 v91, v91, 1.0 op_sel:[1,0,0]
	v_pk_fma_f16 v85, v85, v86, v99
	v_pk_fma_f16 v92, v92, v86, v96
	v_pk_fma_f16 v93, v93, v86, v97
	v_pk_fma_f16 v94, v94, v86, v98
	v_pk_fma_f16 v84, v91, v86, v84
	v_cvt_scalef32_pk_f16_fp8 v86, v80, 1.0
	v_pk_fma_f16 v85, v86, v87, v85
	v_cvt_scalef32_pk_f16_fp8 v80, v80, 1.0 op_sel:[1,0,0]
	v_cvt_scalef32_pk_f16_fp8 v86, v81, 1.0
	v_cvt_scalef32_pk_f16_fp8 v81, v81, 1.0 op_sel:[1,0,0]
	v_pk_fma_f16 v80, v80, v87, v88
	v_pk_fma_f16 v81, v81, v87, v89
	v_cvt_scalef32_pk_f16_fp8 v88, v82, 1.0
	v_cvt_scalef32_pk_f16_fp8 v82, v82, 1.0 op_sel:[1,0,0]
	v_cvt_scalef32_pk_f16_fp8 v89, v83, 1.0
	v_cvt_scalef32_pk_f16_fp8 v83, v83, 1.0 op_sel:[1,0,0]
	v_pk_fma_f16 v86, v86, v87, v92
	v_pk_fma_f16 v88, v88, v87, v93
	v_pk_fma_f16 v82, v82, v87, v90
	v_pk_fma_f16 v89, v89, v87, v94
	v_pk_fma_f16 v83, v83, v87, v84
	v_permlane32_swap_b32_e32 v85, v88
	v_permlane32_swap_b32_e32 v80, v82
	v_permlane32_swap_b32_e32 v86, v89
	v_permlane32_swap_b32_e32 v81, v83
	v_pk_add_f16 v84, v85, v88
	v_pk_add_f16 v80, v80, v82
	v_pk_add_f16 v82, v86, v89
	v_pk_add_f16 v81, v81, v83
	s_nop 0
	v_permlane16_swap_b32_e32 v84, v82
	v_permlane16_swap_b32_e32 v80, v81
	v_pk_add_f16 v82, v84, v82
	v_pk_add_f16 v80, v80, v81
	s_ashr_i32 s9, s8, 31
	v_cndmask_b32_e64 v81, v82, v80, s[2:3]
	v_cndmask_b32_e64 v80, v80, v82, s[2:3]
	s_lshl_b64 s[8:9], s[8:9], 11
	v_mov_b32_dpp v81, v81 row_ror:8 row_mask:0xf bank_mask:0xf bound_ctrl:1
	v_pk_add_f16 v81, v81, v80
	s_add_u32 s16, s14, s8
	v_cvt_f32_f16_e32 v80, v81
	v_cvt_f32_f16_sdwa v81, v81 dst_sel:DWORD dst_unused:UNUSED_PAD src0_sel:WORD_1
	s_addc_u32 s17, s15, s9
	s_lshl_b32 s8, s22, 7
	s_ashr_i32 s9, s8, 31
	v_pk_mul_f32 v[80:81], v[80:81], s[10:11] op_sel_hi:[1,0]
	s_lshl_b64 s[8:9], s[8:9], 1
	v_and_b32_sdwa v83, v80, v208 dst_sel:DWORD dst_unused:UNUSED_PAD src0_sel:WORD_1 src1_sel:DWORD
	v_and_b32_sdwa v82, v81, v208 dst_sel:DWORD dst_unused:UNUSED_PAD src0_sel:WORD_1 src1_sel:DWORD
	v_add3_u32 v80, v80, v83, s7
	s_add_u32 s8, s16, s8
	v_add3_u32 v81, v81, v82, s7
	v_lshrrev_b32_e32 v80, 16, v80
	s_addc_u32 s9, s17, s9
	v_and_or_b32 v82, v81, s11, v80
	v_lshl_add_u64 v[80:81], s[8:9], 0, v[194:195]
	s_add_i32 s8, s24, s19
	s_cmpk_gt_i32 s8, 0x3fff
	s_cselect_b32 s26, s6, s8
	s_cselect_b32 s8, s33, 0
	s_add_i32 s27, s8, s25
	v_mov_b32_e32 v203, v195
	s_cmp_gt_i32 s18, 7
	v_lshl_add_u64 v[80:81], v[80:81], 0, v[202:203]
	s_cselect_b64 s[16:17], -1, 0
	s_mov_b32 s22, s25
	s_mov_b32 s8, s24
	global_store_dword v[80:81], v82, off
	s_branch .LBB0_621
